# DN scan step: decay applied first, both dot products taken on the decayed state (a*dk, a*dq come out directly; 54 instr/step)
# baseline (speedup 1.0000x reference)
.LBB0_906:
	v_readfirstlane_b32 s100, v92
	v_readfirstlane_b32 s101, v93
	s_sub_u32 s100, s100, m0
	s_subb_u32 s101, s101, 0
	s_waitcnt lgkmcnt(0)
	v_pk_mul_f32 v[114:115], v[34:35], v[74:75] op_sel_hi:[0,1]
	v_pk_mul_f32 v[116:117], v[34:35], v[78:79] op_sel_hi:[0,1]
	v_pk_fma_f32 v[106:107], v[114:115], v[2:3], 0 op_sel_hi:[1,1,0]
	v_pk_fma_f32 v[108:109], v[114:115], v[30:31], 0 op_sel_hi:[1,1,0]
	v_pk_mul_f32 v[118:119], v[34:35], v[80:81] op_sel_hi:[0,1]
	ds_read_b128 v[66:69], v94 offset:800
	v_pk_fma_f32 v[106:107], v[116:117], v[4:5], v[106:107]
	v_pk_fma_f32 v[108:109], v[116:117], v[32:33], v[108:109]
	v_pk_mul_f32 v[120:121], v[34:35], v[82:83] op_sel_hi:[0,1]
	ds_read_b128 v[62:65], v94 offset:816
	v_pk_fma_f32 v[106:107], v[118:119], v[6:7], v[106:107]
	v_pk_fma_f32 v[108:109], v[118:119], v[26:27], v[108:109]
	v_pk_mul_f32 v[122:123], v[34:35], v[84:85] op_sel_hi:[0,1]
	ds_read_b128 v[58:61], v94 offset:832
	v_pk_fma_f32 v[106:107], v[120:121], v[8:9], v[106:107]
	v_pk_fma_f32 v[108:109], v[120:121], v[28:29], v[108:109]
	v_pk_mul_f32 v[124:125], v[34:35], v[86:87] op_sel_hi:[0,1]
	ds_read_b128 v[54:57], v94 offset:848
	v_pk_fma_f32 v[106:107], v[122:123], v[14:15], v[106:107]
	v_pk_fma_f32 v[108:109], v[122:123], v[22:23], v[108:109]
	v_pk_mul_f32 v[126:127], v[34:35], v[88:89] op_sel_hi:[0,1]
	ds_read_b128 v[50:53], v94 offset:1056
	v_pk_fma_f32 v[106:107], v[124:125], v[16:17], v[106:107]
	v_pk_fma_f32 v[108:109], v[124:125], v[24:25], v[108:109]
	v_pk_mul_f32 v[128:129], v[34:35], v[90:91] op_sel_hi:[0,1]
	ds_read_b128 v[46:49], v94 offset:1072
	v_pk_fma_f32 v[106:107], v[126:127], v[10:11], v[106:107]
	v_pk_fma_f32 v[108:109], v[126:127], v[18:19], v[108:109]
	ds_read_b128 v[42:45], v94 offset:1088
	v_pk_fma_f32 v[106:107], v[128:129], v[12:13], v[106:107]
	v_pk_fma_f32 v[108:109], v[128:129], v[20:21], v[108:109]
	ds_read_b128 v[38:41], v94 offset:1104
	v_add_f32_e32 v130, v106, v107
	v_add_f32_e32 v131, v108, v109
	ds_read_b32 v0, v95 offset:1312
	v_add_f32_dpp v130, v130, v130 quad_perm:[1,0,3,2] row_mask:0xf bank_mask:0xf bound_ctrl:1
	v_add_f32_dpp v131, v131, v131 quad_perm:[1,0,3,2] row_mask:0xf bank_mask:0xf bound_ctrl:1
	ds_read_b96 v[70:72], v1 offset:1568
	v_add_f32_dpp v130, v130, v130 quad_perm:[2,3,0,1] row_mask:0xf bank_mask:0xf bound_ctrl:1
	v_add_f32_dpp v131, v131, v131 quad_perm:[2,3,0,1] row_mask:0xf bank_mask:0xf bound_ctrl:1
	v_sub_f32_e32 v130, v73, v130
	v_mul_f32_e32 v130, v35, v130
	v_fma_f32 v131, v36, v130, v131
	v_cvt_pk_bf16_f32 v132, v131, v131
	v_pk_fma_f32 v[74:75], v[2:3], v[130:131], v[114:115] op_sel_hi:[1,0,1]
	v_pk_fma_f32 v[78:79], v[4:5], v[130:131], v[116:117] op_sel_hi:[1,0,1]
	global_store_short v144, v132, s[100:101]
	v_pk_fma_f32 v[80:81], v[6:7], v[130:131], v[118:119] op_sel_hi:[1,0,1]
	v_pk_fma_f32 v[82:83], v[8:9], v[130:131], v[120:121] op_sel_hi:[1,0,1]
	v_pk_fma_f32 v[84:85], v[14:15], v[130:131], v[122:123] op_sel_hi:[1,0,1]
	v_pk_fma_f32 v[86:87], v[16:17], v[130:131], v[124:125] op_sel_hi:[1,0,1]
	v_pk_fma_f32 v[88:89], v[10:11], v[130:131], v[126:127] op_sel_hi:[1,0,1]
	v_pk_fma_f32 v[90:91], v[12:13], v[130:131], v[128:129] op_sel_hi:[1,0,1]
	s_waitcnt lgkmcnt(0)
	v_pk_mul_f32 v[114:115], v[70:71], v[74:75] op_sel_hi:[0,1]
	v_pk_mul_f32 v[116:117], v[70:71], v[78:79] op_sel_hi:[0,1]
	v_pk_fma_f32 v[110:111], v[114:115], v[50:51], 0 op_sel_hi:[1,1,0]
	v_pk_fma_f32 v[112:113], v[114:115], v[66:67], 0 op_sel_hi:[1,1,0]
	v_pk_mul_f32 v[118:119], v[70:71], v[80:81] op_sel_hi:[0,1]
	ds_read_b128 v[30:33], v94 offset:1600
	v_pk_fma_f32 v[110:111], v[116:117], v[52:53], v[110:111]
	v_pk_fma_f32 v[112:113], v[116:117], v[68:69], v[112:113]
	v_pk_mul_f32 v[120:121], v[70:71], v[82:83] op_sel_hi:[0,1]
	ds_read_b128 v[26:29], v94 offset:1616
	v_pk_fma_f32 v[110:111], v[118:119], v[46:47], v[110:111]
	v_pk_fma_f32 v[112:113], v[118:119], v[62:63], v[112:113]
	v_pk_mul_f32 v[122:123], v[70:71], v[84:85] op_sel_hi:[0,1]
	ds_read_b128 v[22:25], v94 offset:1632
	v_pk_fma_f32 v[110:111], v[120:121], v[48:49], v[110:111]
	v_pk_fma_f32 v[112:113], v[120:121], v[64:65], v[112:113]
	v_pk_mul_f32 v[124:125], v[70:71], v[86:87] op_sel_hi:[0,1]
	ds_read_b128 v[18:21], v94 offset:1648
	v_pk_fma_f32 v[110:111], v[122:123], v[42:43], v[110:111]
	v_pk_fma_f32 v[112:113], v[122:123], v[58:59], v[112:113]
	v_pk_mul_f32 v[126:127], v[70:71], v[88:89] op_sel_hi:[0,1]
	ds_read_b128 v[2:5], v94 offset:1856
	v_pk_fma_f32 v[110:111], v[124:125], v[44:45], v[110:111]
	v_pk_fma_f32 v[112:113], v[124:125], v[60:61], v[112:113]
	v_pk_mul_f32 v[128:129], v[70:71], v[90:91] op_sel_hi:[0,1]
	ds_read_b128 v[6:9], v94 offset:1872
	v_pk_fma_f32 v[110:111], v[126:127], v[38:39], v[110:111]
	v_pk_fma_f32 v[112:113], v[126:127], v[54:55], v[112:113]
	ds_read_b128 v[14:17], v94 offset:1888
	v_pk_fma_f32 v[110:111], v[128:129], v[40:41], v[110:111]
	v_pk_fma_f32 v[112:113], v[128:129], v[56:57], v[112:113]
	ds_read_b128 v[10:13], v94 offset:1904
	v_add_f32_e32 v134, v110, v111
	v_add_f32_e32 v135, v112, v113
	ds_read_b32 v73, v95 offset:2112
	v_add_f32_dpp v134, v134, v134 quad_perm:[1,0,3,2] row_mask:0xf bank_mask:0xf bound_ctrl:1
	v_add_f32_dpp v135, v135, v135 quad_perm:[1,0,3,2] row_mask:0xf bank_mask:0xf bound_ctrl:1
	ds_read_b96 v[34:36], v1 offset:2368
	v_add_f32_dpp v134, v134, v134 quad_perm:[2,3,0,1] row_mask:0xf bank_mask:0xf bound_ctrl:1
	v_add_f32_dpp v135, v135, v135 quad_perm:[2,3,0,1] row_mask:0xf bank_mask:0xf bound_ctrl:1
	v_sub_f32_e32 v134, v0, v134
	v_mul_f32_e32 v134, v71, v134
	v_fma_f32 v135, v72, v134, v135
	v_cvt_pk_bf16_f32 v133, v135, v135
	v_pk_fma_f32 v[74:75], v[50:51], v[134:135], v[114:115] op_sel_hi:[1,0,1]
	v_pk_fma_f32 v[78:79], v[52:53], v[134:135], v[116:117] op_sel_hi:[1,0,1]
	global_store_short v145, v133, s[100:101]
	v_pk_fma_f32 v[80:81], v[46:47], v[134:135], v[118:119] op_sel_hi:[1,0,1]
	v_pk_fma_f32 v[82:83], v[48:49], v[134:135], v[120:121] op_sel_hi:[1,0,1]
	v_pk_fma_f32 v[84:85], v[42:43], v[134:135], v[122:123] op_sel_hi:[1,0,1]
	v_pk_fma_f32 v[86:87], v[44:45], v[134:135], v[124:125] op_sel_hi:[1,0,1]
	v_pk_fma_f32 v[88:89], v[38:39], v[134:135], v[126:127] op_sel_hi:[1,0,1]
	v_pk_fma_f32 v[90:91], v[40:41], v[134:135], v[128:129] op_sel_hi:[1,0,1]
	s_waitcnt lgkmcnt(0)
	v_pk_mul_f32 v[114:115], v[34:35], v[74:75] op_sel_hi:[0,1]
	v_pk_mul_f32 v[116:117], v[34:35], v[78:79] op_sel_hi:[0,1]
	v_pk_fma_f32 v[106:107], v[114:115], v[2:3], 0 op_sel_hi:[1,1,0]
	v_pk_fma_f32 v[108:109], v[114:115], v[30:31], 0 op_sel_hi:[1,1,0]
	v_pk_mul_f32 v[118:119], v[34:35], v[80:81] op_sel_hi:[0,1]
	ds_read_b128 v[66:69], v94 offset:2400
	v_pk_fma_f32 v[106:107], v[116:117], v[4:5], v[106:107]
	v_pk_fma_f32 v[108:109], v[116:117], v[32:33], v[108:109]
	v_pk_mul_f32 v[120:121], v[34:35], v[82:83] op_sel_hi:[0,1]
	ds_read_b128 v[62:65], v94 offset:2416
	v_pk_fma_f32 v[106:107], v[118:119], v[6:7], v[106:107]
	v_pk_fma_f32 v[108:109], v[118:119], v[26:27], v[108:109]
	v_pk_mul_f32 v[122:123], v[34:35], v[84:85] op_sel_hi:[0,1]
	ds_read_b128 v[58:61], v94 offset:2432
	v_pk_fma_f32 v[106:107], v[120:121], v[8:9], v[106:107]
	v_pk_fma_f32 v[108:109], v[120:121], v[28:29], v[108:109]
	v_pk_mul_f32 v[124:125], v[34:35], v[86:87] op_sel_hi:[0,1]
	ds_read_b128 v[54:57], v94 offset:2448
	v_pk_fma_f32 v[106:107], v[122:123], v[14:15], v[106:107]
	v_pk_fma_f32 v[108:109], v[122:123], v[22:23], v[108:109]
	v_pk_mul_f32 v[126:127], v[34:35], v[88:89] op_sel_hi:[0,1]
	ds_read_b128 v[50:53], v94 offset:2656
	v_pk_fma_f32 v[106:107], v[124:125], v[16:17], v[106:107]
	v_pk_fma_f32 v[108:109], v[124:125], v[24:25], v[108:109]
	v_pk_mul_f32 v[128:129], v[34:35], v[90:91] op_sel_hi:[0,1]
	ds_read_b128 v[46:49], v94 offset:2672
	v_pk_fma_f32 v[106:107], v[126:127], v[10:11], v[106:107]
	v_pk_fma_f32 v[108:109], v[126:127], v[18:19], v[108:109]
	ds_read_b128 v[42:45], v94 offset:2688
	v_pk_fma_f32 v[106:107], v[128:129], v[12:13], v[106:107]
	v_pk_fma_f32 v[108:109], v[128:129], v[20:21], v[108:109]
	ds_read_b128 v[38:41], v94 offset:2704
	v_add_f32_e32 v130, v106, v107
	v_add_f32_e32 v131, v108, v109
	ds_read_b32 v0, v95 offset:2912
	v_add_f32_dpp v130, v130, v130 quad_perm:[1,0,3,2] row_mask:0xf bank_mask:0xf bound_ctrl:1
	v_add_f32_dpp v131, v131, v131 quad_perm:[1,0,3,2] row_mask:0xf bank_mask:0xf bound_ctrl:1
	ds_read_b96 v[70:72], v1 offset:3168
	v_add_f32_dpp v130, v130, v130 quad_perm:[2,3,0,1] row_mask:0xf bank_mask:0xf bound_ctrl:1
	v_add_f32_dpp v131, v131, v131 quad_perm:[2,3,0,1] row_mask:0xf bank_mask:0xf bound_ctrl:1
	v_sub_f32_e32 v130, v73, v130
	v_mul_f32_e32 v130, v35, v130
	v_fma_f32 v131, v36, v130, v131
	v_cvt_pk_bf16_f32 v132, v131, v131
	v_pk_fma_f32 v[74:75], v[2:3], v[130:131], v[114:115] op_sel_hi:[1,0,1]
	v_pk_fma_f32 v[78:79], v[4:5], v[130:131], v[116:117] op_sel_hi:[1,0,1]
	global_store_short v146, v132, s[100:101]
	v_pk_fma_f32 v[80:81], v[6:7], v[130:131], v[118:119] op_sel_hi:[1,0,1]
	v_pk_fma_f32 v[82:83], v[8:9], v[130:131], v[120:121] op_sel_hi:[1,0,1]
	v_pk_fma_f32 v[84:85], v[14:15], v[130:131], v[122:123] op_sel_hi:[1,0,1]
	v_pk_fma_f32 v[86:87], v[16:17], v[130:131], v[124:125] op_sel_hi:[1,0,1]
	v_pk_fma_f32 v[88:89], v[10:11], v[130:131], v[126:127] op_sel_hi:[1,0,1]
	v_pk_fma_f32 v[90:91], v[12:13], v[130:131], v[128:129] op_sel_hi:[1,0,1]
	s_waitcnt lgkmcnt(0)
	v_pk_mul_f32 v[114:115], v[70:71], v[74:75] op_sel_hi:[0,1]
	v_pk_mul_f32 v[116:117], v[70:71], v[78:79] op_sel_hi:[0,1]
	v_pk_fma_f32 v[110:111], v[114:115], v[50:51], 0 op_sel_hi:[1,1,0]
	v_pk_fma_f32 v[112:113], v[114:115], v[66:67], 0 op_sel_hi:[1,1,0]
	v_pk_mul_f32 v[118:119], v[70:71], v[80:81] op_sel_hi:[0,1]
	ds_read_b128 v[30:33], v94 offset:3200
	v_pk_fma_f32 v[110:111], v[116:117], v[52:53], v[110:111]
	v_pk_fma_f32 v[112:113], v[116:117], v[68:69], v[112:113]
	v_pk_mul_f32 v[120:121], v[70:71], v[82:83] op_sel_hi:[0,1]
	ds_read_b128 v[26:29], v94 offset:3216
	v_pk_fma_f32 v[110:111], v[118:119], v[46:47], v[110:111]
	v_pk_fma_f32 v[112:113], v[118:119], v[62:63], v[112:113]
	v_pk_mul_f32 v[122:123], v[70:71], v[84:85] op_sel_hi:[0,1]
	ds_read_b128 v[22:25], v94 offset:3232
	v_pk_fma_f32 v[110:111], v[120:121], v[48:49], v[110:111]
	v_pk_fma_f32 v[112:113], v[120:121], v[64:65], v[112:113]
	v_pk_mul_f32 v[124:125], v[70:71], v[86:87] op_sel_hi:[0,1]
	ds_read_b128 v[18:21], v94 offset:3248
	v_pk_fma_f32 v[110:111], v[122:123], v[42:43], v[110:111]
	v_pk_fma_f32 v[112:113], v[122:123], v[58:59], v[112:113]
	v_pk_mul_f32 v[126:127], v[70:71], v[88:89] op_sel_hi:[0,1]
	ds_read_b128 v[2:5], v94 offset:3456
	v_pk_fma_f32 v[110:111], v[124:125], v[44:45], v[110:111]
	v_pk_fma_f32 v[112:113], v[124:125], v[60:61], v[112:113]
	v_pk_mul_f32 v[128:129], v[70:71], v[90:91] op_sel_hi:[0,1]
	ds_read_b128 v[6:9], v94 offset:3472
	v_pk_fma_f32 v[110:111], v[126:127], v[38:39], v[110:111]
	v_pk_fma_f32 v[112:113], v[126:127], v[54:55], v[112:113]
	ds_read_b128 v[14:17], v94 offset:3488
	v_pk_fma_f32 v[110:111], v[128:129], v[40:41], v[110:111]
	v_pk_fma_f32 v[112:113], v[128:129], v[56:57], v[112:113]
	ds_read_b128 v[10:13], v94 offset:3504
	v_add_f32_e32 v134, v110, v111
	v_add_f32_e32 v135, v112, v113
	ds_read_b32 v73, v95 offset:3712
	v_add_f32_dpp v134, v134, v134 quad_perm:[1,0,3,2] row_mask:0xf bank_mask:0xf bound_ctrl:1
	v_add_f32_dpp v135, v135, v135 quad_perm:[1,0,3,2] row_mask:0xf bank_mask:0xf bound_ctrl:1
	ds_read_b96 v[34:36], v1 offset:3968
	v_add_f32_dpp v134, v134, v134 quad_perm:[2,3,0,1] row_mask:0xf bank_mask:0xf bound_ctrl:1
	v_add_f32_dpp v135, v135, v135 quad_perm:[2,3,0,1] row_mask:0xf bank_mask:0xf bound_ctrl:1
	v_sub_f32_e32 v134, v0, v134
	v_mul_f32_e32 v134, v71, v134
	v_fma_f32 v135, v72, v134, v135
	v_cvt_pk_bf16_f32 v133, v135, v135
	v_pk_fma_f32 v[74:75], v[50:51], v[134:135], v[114:115] op_sel_hi:[1,0,1]
	v_pk_fma_f32 v[78:79], v[52:53], v[134:135], v[116:117] op_sel_hi:[1,0,1]
	global_store_short v147, v133, s[100:101]
	v_pk_fma_f32 v[80:81], v[46:47], v[134:135], v[118:119] op_sel_hi:[1,0,1]
	v_pk_fma_f32 v[82:83], v[48:49], v[134:135], v[120:121] op_sel_hi:[1,0,1]
	v_pk_fma_f32 v[84:85], v[42:43], v[134:135], v[122:123] op_sel_hi:[1,0,1]
	v_pk_fma_f32 v[86:87], v[44:45], v[134:135], v[124:125] op_sel_hi:[1,0,1]
	v_pk_fma_f32 v[88:89], v[38:39], v[134:135], v[126:127] op_sel_hi:[1,0,1]
	v_pk_fma_f32 v[90:91], v[40:41], v[134:135], v[128:129] op_sel_hi:[1,0,1]
	s_waitcnt lgkmcnt(0)
	v_pk_mul_f32 v[114:115], v[34:35], v[74:75] op_sel_hi:[0,1]
	v_pk_mul_f32 v[116:117], v[34:35], v[78:79] op_sel_hi:[0,1]
	v_pk_fma_f32 v[106:107], v[114:115], v[2:3], 0 op_sel_hi:[1,1,0]
	v_pk_fma_f32 v[108:109], v[114:115], v[30:31], 0 op_sel_hi:[1,1,0]
	v_pk_mul_f32 v[118:119], v[34:35], v[80:81] op_sel_hi:[0,1]
	ds_read_b128 v[66:69], v94 offset:4000
	v_pk_fma_f32 v[106:107], v[116:117], v[4:5], v[106:107]
	v_pk_fma_f32 v[108:109], v[116:117], v[32:33], v[108:109]
	v_pk_mul_f32 v[120:121], v[34:35], v[82:83] op_sel_hi:[0,1]
	ds_read_b128 v[62:65], v94 offset:4016
	v_pk_fma_f32 v[106:107], v[118:119], v[6:7], v[106:107]
	v_pk_fma_f32 v[108:109], v[118:119], v[26:27], v[108:109]
	v_pk_mul_f32 v[122:123], v[34:35], v[84:85] op_sel_hi:[0,1]
	ds_read_b128 v[58:61], v94 offset:4032
	v_pk_fma_f32 v[106:107], v[120:121], v[8:9], v[106:107]
	v_pk_fma_f32 v[108:109], v[120:121], v[28:29], v[108:109]
	v_pk_mul_f32 v[124:125], v[34:35], v[86:87] op_sel_hi:[0,1]
	ds_read_b128 v[54:57], v94 offset:4048
	v_pk_fma_f32 v[106:107], v[122:123], v[14:15], v[106:107]
	v_pk_fma_f32 v[108:109], v[122:123], v[22:23], v[108:109]
	v_pk_mul_f32 v[126:127], v[34:35], v[88:89] op_sel_hi:[0,1]
	ds_read_b128 v[50:53], v94 offset:4256
	v_pk_fma_f32 v[106:107], v[124:125], v[16:17], v[106:107]
	v_pk_fma_f32 v[108:109], v[124:125], v[24:25], v[108:109]
	v_pk_mul_f32 v[128:129], v[34:35], v[90:91] op_sel_hi:[0,1]
	ds_read_b128 v[46:49], v94 offset:4272
	v_pk_fma_f32 v[106:107], v[126:127], v[10:11], v[106:107]
	v_pk_fma_f32 v[108:109], v[126:127], v[18:19], v[108:109]
	ds_read_b128 v[42:45], v94 offset:4288
	v_pk_fma_f32 v[106:107], v[128:129], v[12:13], v[106:107]
	v_pk_fma_f32 v[108:109], v[128:129], v[20:21], v[108:109]
	ds_read_b128 v[38:41], v94 offset:4304
	v_add_f32_e32 v130, v106, v107
	v_add_f32_e32 v131, v108, v109
	ds_read_b32 v0, v95 offset:4512
	v_add_f32_dpp v130, v130, v130 quad_perm:[1,0,3,2] row_mask:0xf bank_mask:0xf bound_ctrl:1
	v_add_f32_dpp v131, v131, v131 quad_perm:[1,0,3,2] row_mask:0xf bank_mask:0xf bound_ctrl:1
	ds_read_b96 v[70:72], v1 offset:4768
	v_add_f32_dpp v130, v130, v130 quad_perm:[2,3,0,1] row_mask:0xf bank_mask:0xf bound_ctrl:1
	v_add_f32_dpp v131, v131, v131 quad_perm:[2,3,0,1] row_mask:0xf bank_mask:0xf bound_ctrl:1
	v_sub_f32_e32 v130, v73, v130
	v_mul_f32_e32 v130, v35, v130
	v_fma_f32 v131, v36, v130, v131
	v_cvt_pk_bf16_f32 v132, v131, v131
	v_pk_fma_f32 v[74:75], v[2:3], v[130:131], v[114:115] op_sel_hi:[1,0,1]
	v_pk_fma_f32 v[78:79], v[4:5], v[130:131], v[116:117] op_sel_hi:[1,0,1]
	global_store_short v148, v132, s[100:101]
	v_pk_fma_f32 v[80:81], v[6:7], v[130:131], v[118:119] op_sel_hi:[1,0,1]
	v_pk_fma_f32 v[82:83], v[8:9], v[130:131], v[120:121] op_sel_hi:[1,0,1]
	v_pk_fma_f32 v[84:85], v[14:15], v[130:131], v[122:123] op_sel_hi:[1,0,1]
	v_pk_fma_f32 v[86:87], v[16:17], v[130:131], v[124:125] op_sel_hi:[1,0,1]
	v_pk_fma_f32 v[88:89], v[10:11], v[130:131], v[126:127] op_sel_hi:[1,0,1]
	v_pk_fma_f32 v[90:91], v[12:13], v[130:131], v[128:129] op_sel_hi:[1,0,1]
	s_waitcnt lgkmcnt(0)
	v_pk_mul_f32 v[114:115], v[70:71], v[74:75] op_sel_hi:[0,1]
	v_pk_mul_f32 v[116:117], v[70:71], v[78:79] op_sel_hi:[0,1]
	v_pk_fma_f32 v[110:111], v[114:115], v[50:51], 0 op_sel_hi:[1,1,0]
	v_pk_fma_f32 v[112:113], v[114:115], v[66:67], 0 op_sel_hi:[1,1,0]
	v_pk_mul_f32 v[118:119], v[70:71], v[80:81] op_sel_hi:[0,1]
	ds_read_b128 v[30:33], v94 offset:4800
	v_pk_fma_f32 v[110:111], v[116:117], v[52:53], v[110:111]
	v_pk_fma_f32 v[112:113], v[116:117], v[68:69], v[112:113]
	v_pk_mul_f32 v[120:121], v[70:71], v[82:83] op_sel_hi:[0,1]
	ds_read_b128 v[26:29], v94 offset:4816
	v_pk_fma_f32 v[110:111], v[118:119], v[46:47], v[110:111]
	v_pk_fma_f32 v[112:113], v[118:119], v[62:63], v[112:113]
	v_pk_mul_f32 v[122:123], v[70:71], v[84:85] op_sel_hi:[0,1]
	ds_read_b128 v[22:25], v94 offset:4832
	v_pk_fma_f32 v[110:111], v[120:121], v[48:49], v[110:111]
	v_pk_fma_f32 v[112:113], v[120:121], v[64:65], v[112:113]
	v_pk_mul_f32 v[124:125], v[70:71], v[86:87] op_sel_hi:[0,1]
	ds_read_b128 v[18:21], v94 offset:4848
	v_pk_fma_f32 v[110:111], v[122:123], v[42:43], v[110:111]
	v_pk_fma_f32 v[112:113], v[122:123], v[58:59], v[112:113]
	v_pk_mul_f32 v[126:127], v[70:71], v[88:89] op_sel_hi:[0,1]
	ds_read_b128 v[2:5], v94 offset:5056
	v_pk_fma_f32 v[110:111], v[124:125], v[44:45], v[110:111]
	v_pk_fma_f32 v[112:113], v[124:125], v[60:61], v[112:113]
	v_pk_mul_f32 v[128:129], v[70:71], v[90:91] op_sel_hi:[0,1]
	ds_read_b128 v[6:9], v94 offset:5072
	v_pk_fma_f32 v[110:111], v[126:127], v[38:39], v[110:111]
	v_pk_fma_f32 v[112:113], v[126:127], v[54:55], v[112:113]
	ds_read_b128 v[14:17], v94 offset:5088
	v_pk_fma_f32 v[110:111], v[128:129], v[40:41], v[110:111]
	v_pk_fma_f32 v[112:113], v[128:129], v[56:57], v[112:113]
	ds_read_b128 v[10:13], v94 offset:5104
	v_add_f32_e32 v134, v110, v111
	v_add_f32_e32 v135, v112, v113
	ds_read_b32 v73, v95 offset:5312
	v_add_f32_dpp v134, v134, v134 quad_perm:[1,0,3,2] row_mask:0xf bank_mask:0xf bound_ctrl:1
	v_add_f32_dpp v135, v135, v135 quad_perm:[1,0,3,2] row_mask:0xf bank_mask:0xf bound_ctrl:1
	ds_read_b96 v[34:36], v1 offset:5568
	v_add_f32_dpp v134, v134, v134 quad_perm:[2,3,0,1] row_mask:0xf bank_mask:0xf bound_ctrl:1
	v_add_f32_dpp v135, v135, v135 quad_perm:[2,3,0,1] row_mask:0xf bank_mask:0xf bound_ctrl:1
	v_sub_f32_e32 v134, v0, v134
	v_mul_f32_e32 v134, v71, v134
	v_fma_f32 v135, v72, v134, v135
	v_cvt_pk_bf16_f32 v133, v135, v135
	v_pk_fma_f32 v[74:75], v[50:51], v[134:135], v[114:115] op_sel_hi:[1,0,1]
	v_pk_fma_f32 v[78:79], v[52:53], v[134:135], v[116:117] op_sel_hi:[1,0,1]
	global_store_short v149, v133, s[100:101]
	v_pk_fma_f32 v[80:81], v[46:47], v[134:135], v[118:119] op_sel_hi:[1,0,1]
	v_pk_fma_f32 v[82:83], v[48:49], v[134:135], v[120:121] op_sel_hi:[1,0,1]
	v_pk_fma_f32 v[84:85], v[42:43], v[134:135], v[122:123] op_sel_hi:[1,0,1]
	v_pk_fma_f32 v[86:87], v[44:45], v[134:135], v[124:125] op_sel_hi:[1,0,1]
	v_pk_fma_f32 v[88:89], v[38:39], v[134:135], v[126:127] op_sel_hi:[1,0,1]
	v_pk_fma_f32 v[90:91], v[40:41], v[134:135], v[128:129] op_sel_hi:[1,0,1]
	s_waitcnt lgkmcnt(0)
	v_pk_mul_f32 v[114:115], v[34:35], v[74:75] op_sel_hi:[0,1]
	v_pk_mul_f32 v[116:117], v[34:35], v[78:79] op_sel_hi:[0,1]
	v_pk_fma_f32 v[106:107], v[114:115], v[2:3], 0 op_sel_hi:[1,1,0]
	v_pk_fma_f32 v[108:109], v[114:115], v[30:31], 0 op_sel_hi:[1,1,0]
	v_pk_mul_f32 v[118:119], v[34:35], v[80:81] op_sel_hi:[0,1]
	ds_read_b128 v[66:69], v94 offset:5600
	v_pk_fma_f32 v[106:107], v[116:117], v[4:5], v[106:107]
	v_pk_fma_f32 v[108:109], v[116:117], v[32:33], v[108:109]
	v_pk_mul_f32 v[120:121], v[34:35], v[82:83] op_sel_hi:[0,1]
	ds_read_b128 v[62:65], v94 offset:5616
	v_pk_fma_f32 v[106:107], v[118:119], v[6:7], v[106:107]
	v_pk_fma_f32 v[108:109], v[118:119], v[26:27], v[108:109]
	v_pk_mul_f32 v[122:123], v[34:35], v[84:85] op_sel_hi:[0,1]
	ds_read_b128 v[58:61], v94 offset:5632
	v_pk_fma_f32 v[106:107], v[120:121], v[8:9], v[106:107]
	v_pk_fma_f32 v[108:109], v[120:121], v[28:29], v[108:109]
	v_pk_mul_f32 v[124:125], v[34:35], v[86:87] op_sel_hi:[0,1]
	ds_read_b128 v[54:57], v94 offset:5648
	v_pk_fma_f32 v[106:107], v[122:123], v[14:15], v[106:107]
	v_pk_fma_f32 v[108:109], v[122:123], v[22:23], v[108:109]
	v_pk_mul_f32 v[126:127], v[34:35], v[88:89] op_sel_hi:[0,1]
	ds_read_b128 v[50:53], v94 offset:5856
	v_pk_fma_f32 v[106:107], v[124:125], v[16:17], v[106:107]
	v_pk_fma_f32 v[108:109], v[124:125], v[24:25], v[108:109]
	v_pk_mul_f32 v[128:129], v[34:35], v[90:91] op_sel_hi:[0,1]
	ds_read_b128 v[46:49], v94 offset:5872
	v_pk_fma_f32 v[106:107], v[126:127], v[10:11], v[106:107]
	v_pk_fma_f32 v[108:109], v[126:127], v[18:19], v[108:109]
	ds_read_b128 v[42:45], v94 offset:5888
	v_pk_fma_f32 v[106:107], v[128:129], v[12:13], v[106:107]
	v_pk_fma_f32 v[108:109], v[128:129], v[20:21], v[108:109]
	ds_read_b128 v[38:41], v94 offset:5904
	v_add_f32_e32 v130, v106, v107
	v_add_f32_e32 v131, v108, v109
	ds_read_b32 v0, v95 offset:6112
	v_add_f32_dpp v130, v130, v130 quad_perm:[1,0,3,2] row_mask:0xf bank_mask:0xf bound_ctrl:1
	v_add_f32_dpp v131, v131, v131 quad_perm:[1,0,3,2] row_mask:0xf bank_mask:0xf bound_ctrl:1
	ds_read_b96 v[70:72], v1 offset:6368
	v_add_f32_dpp v130, v130, v130 quad_perm:[2,3,0,1] row_mask:0xf bank_mask:0xf bound_ctrl:1
	v_add_f32_dpp v131, v131, v131 quad_perm:[2,3,0,1] row_mask:0xf bank_mask:0xf bound_ctrl:1
	v_sub_f32_e32 v130, v73, v130
	v_mul_f32_e32 v130, v35, v130
	v_fma_f32 v131, v36, v130, v131
	v_cvt_pk_bf16_f32 v132, v131, v131
	v_pk_fma_f32 v[74:75], v[2:3], v[130:131], v[114:115] op_sel_hi:[1,0,1]
	v_pk_fma_f32 v[78:79], v[4:5], v[130:131], v[116:117] op_sel_hi:[1,0,1]
	global_store_short v150, v132, s[100:101]
	v_pk_fma_f32 v[80:81], v[6:7], v[130:131], v[118:119] op_sel_hi:[1,0,1]
	v_pk_fma_f32 v[82:83], v[8:9], v[130:131], v[120:121] op_sel_hi:[1,0,1]
	v_pk_fma_f32 v[84:85], v[14:15], v[130:131], v[122:123] op_sel_hi:[1,0,1]
	v_pk_fma_f32 v[86:87], v[16:17], v[130:131], v[124:125] op_sel_hi:[1,0,1]
	v_pk_fma_f32 v[88:89], v[10:11], v[130:131], v[126:127] op_sel_hi:[1,0,1]
	v_pk_fma_f32 v[90:91], v[12:13], v[130:131], v[128:129] op_sel_hi:[1,0,1]
	s_waitcnt lgkmcnt(0)
	v_pk_mul_f32 v[114:115], v[70:71], v[74:75] op_sel_hi:[0,1]
	v_pk_mul_f32 v[116:117], v[70:71], v[78:79] op_sel_hi:[0,1]
	v_pk_fma_f32 v[110:111], v[114:115], v[50:51], 0 op_sel_hi:[1,1,0]
	v_pk_fma_f32 v[112:113], v[114:115], v[66:67], 0 op_sel_hi:[1,1,0]
	v_pk_mul_f32 v[118:119], v[70:71], v[80:81] op_sel_hi:[0,1]
	ds_read_b128 v[30:33], v94 offset:6400
	v_pk_fma_f32 v[110:111], v[116:117], v[52:53], v[110:111]
	v_pk_fma_f32 v[112:113], v[116:117], v[68:69], v[112:113]
	v_pk_mul_f32 v[120:121], v[70:71], v[82:83] op_sel_hi:[0,1]
	ds_read_b128 v[26:29], v94 offset:6416
	v_pk_fma_f32 v[110:111], v[118:119], v[46:47], v[110:111]
	v_pk_fma_f32 v[112:113], v[118:119], v[62:63], v[112:113]
	v_pk_mul_f32 v[122:123], v[70:71], v[84:85] op_sel_hi:[0,1]
	ds_read_b128 v[22:25], v94 offset:6432
	v_pk_fma_f32 v[110:111], v[120:121], v[48:49], v[110:111]
	v_pk_fma_f32 v[112:113], v[120:121], v[64:65], v[112:113]
	v_pk_mul_f32 v[124:125], v[70:71], v[86:87] op_sel_hi:[0,1]
	ds_read_b128 v[18:21], v94 offset:6448
	v_pk_fma_f32 v[110:111], v[122:123], v[42:43], v[110:111]
	v_pk_fma_f32 v[112:113], v[122:123], v[58:59], v[112:113]
	v_pk_mul_f32 v[126:127], v[70:71], v[88:89] op_sel_hi:[0,1]
	ds_read_b128 v[2:5], v94 offset:6656
	v_pk_fma_f32 v[110:111], v[124:125], v[44:45], v[110:111]
	v_pk_fma_f32 v[112:113], v[124:125], v[60:61], v[112:113]
	v_pk_mul_f32 v[128:129], v[70:71], v[90:91] op_sel_hi:[0,1]
	ds_read_b128 v[6:9], v94 offset:6672
	v_pk_fma_f32 v[110:111], v[126:127], v[38:39], v[110:111]
	v_pk_fma_f32 v[112:113], v[126:127], v[54:55], v[112:113]
	ds_read_b128 v[14:17], v94 offset:6688
	v_pk_fma_f32 v[110:111], v[128:129], v[40:41], v[110:111]
	v_pk_fma_f32 v[112:113], v[128:129], v[56:57], v[112:113]
	ds_read_b128 v[10:13], v94 offset:6704
	v_add_f32_e32 v134, v110, v111
	v_add_f32_e32 v135, v112, v113
	ds_read_b32 v73, v95 offset:6912
	v_add_f32_dpp v134, v134, v134 quad_perm:[1,0,3,2] row_mask:0xf bank_mask:0xf bound_ctrl:1
	v_add_f32_dpp v135, v135, v135 quad_perm:[1,0,3,2] row_mask:0xf bank_mask:0xf bound_ctrl:1
	ds_read_b96 v[34:36], v1 offset:7168
	v_add_f32_dpp v134, v134, v134 quad_perm:[2,3,0,1] row_mask:0xf bank_mask:0xf bound_ctrl:1
	v_add_f32_dpp v135, v135, v135 quad_perm:[2,3,0,1] row_mask:0xf bank_mask:0xf bound_ctrl:1
	v_sub_f32_e32 v134, v0, v134
	v_mul_f32_e32 v134, v71, v134
	v_fma_f32 v135, v72, v134, v135
	v_cvt_pk_bf16_f32 v133, v135, v135
	v_pk_fma_f32 v[74:75], v[50:51], v[134:135], v[114:115] op_sel_hi:[1,0,1]
	v_pk_fma_f32 v[78:79], v[52:53], v[134:135], v[116:117] op_sel_hi:[1,0,1]
	global_store_short v151, v133, s[100:101]
	v_pk_fma_f32 v[80:81], v[46:47], v[134:135], v[118:119] op_sel_hi:[1,0,1]
	v_pk_fma_f32 v[82:83], v[48:49], v[134:135], v[120:121] op_sel_hi:[1,0,1]
	v_pk_fma_f32 v[84:85], v[42:43], v[134:135], v[122:123] op_sel_hi:[1,0,1]
	v_pk_fma_f32 v[86:87], v[44:45], v[134:135], v[124:125] op_sel_hi:[1,0,1]
	v_pk_fma_f32 v[88:89], v[38:39], v[134:135], v[126:127] op_sel_hi:[1,0,1]
	v_pk_fma_f32 v[90:91], v[40:41], v[134:135], v[128:129] op_sel_hi:[1,0,1]
	s_waitcnt lgkmcnt(0)
	v_pk_mul_f32 v[114:115], v[34:35], v[74:75] op_sel_hi:[0,1]
	v_pk_mul_f32 v[116:117], v[34:35], v[78:79] op_sel_hi:[0,1]
	v_pk_fma_f32 v[106:107], v[114:115], v[2:3], 0 op_sel_hi:[1,1,0]
	v_pk_fma_f32 v[108:109], v[114:115], v[30:31], 0 op_sel_hi:[1,1,0]
	v_pk_mul_f32 v[118:119], v[34:35], v[80:81] op_sel_hi:[0,1]
	ds_read_b128 v[66:69], v94 offset:7200
	v_pk_fma_f32 v[106:107], v[116:117], v[4:5], v[106:107]
	v_pk_fma_f32 v[108:109], v[116:117], v[32:33], v[108:109]
	v_pk_mul_f32 v[120:121], v[34:35], v[82:83] op_sel_hi:[0,1]
	ds_read_b128 v[62:65], v94 offset:7216
	v_pk_fma_f32 v[106:107], v[118:119], v[6:7], v[106:107]
	v_pk_fma_f32 v[108:109], v[118:119], v[26:27], v[108:109]
	v_pk_mul_f32 v[122:123], v[34:35], v[84:85] op_sel_hi:[0,1]
	ds_read_b128 v[58:61], v94 offset:7232
	v_pk_fma_f32 v[106:107], v[120:121], v[8:9], v[106:107]
	v_pk_fma_f32 v[108:109], v[120:121], v[28:29], v[108:109]
	v_pk_mul_f32 v[124:125], v[34:35], v[86:87] op_sel_hi:[0,1]
	ds_read_b128 v[54:57], v94 offset:7248
	v_pk_fma_f32 v[106:107], v[122:123], v[14:15], v[106:107]
	v_pk_fma_f32 v[108:109], v[122:123], v[22:23], v[108:109]
	v_pk_mul_f32 v[126:127], v[34:35], v[88:89] op_sel_hi:[0,1]
	ds_read_b128 v[50:53], v94 offset:7456
	v_pk_fma_f32 v[106:107], v[124:125], v[16:17], v[106:107]
	v_pk_fma_f32 v[108:109], v[124:125], v[24:25], v[108:109]
	v_pk_mul_f32 v[128:129], v[34:35], v[90:91] op_sel_hi:[0,1]
	ds_read_b128 v[46:49], v94 offset:7472
	v_pk_fma_f32 v[106:107], v[126:127], v[10:11], v[106:107]
	v_pk_fma_f32 v[108:109], v[126:127], v[18:19], v[108:109]
	ds_read_b128 v[42:45], v94 offset:7488
	v_pk_fma_f32 v[106:107], v[128:129], v[12:13], v[106:107]
	v_pk_fma_f32 v[108:109], v[128:129], v[20:21], v[108:109]
	ds_read_b128 v[38:41], v94 offset:7504
	v_add_f32_e32 v130, v106, v107
	v_add_f32_e32 v131, v108, v109
	ds_read_b32 v0, v95 offset:7712
	v_add_f32_dpp v130, v130, v130 quad_perm:[1,0,3,2] row_mask:0xf bank_mask:0xf bound_ctrl:1
	v_add_f32_dpp v131, v131, v131 quad_perm:[1,0,3,2] row_mask:0xf bank_mask:0xf bound_ctrl:1
	ds_read_b96 v[70:72], v1 offset:7968
	v_add_f32_dpp v130, v130, v130 quad_perm:[2,3,0,1] row_mask:0xf bank_mask:0xf bound_ctrl:1
	v_add_f32_dpp v131, v131, v131 quad_perm:[2,3,0,1] row_mask:0xf bank_mask:0xf bound_ctrl:1
	v_sub_f32_e32 v130, v73, v130
	v_mul_f32_e32 v130, v35, v130
	v_fma_f32 v131, v36, v130, v131
	v_cvt_pk_bf16_f32 v132, v131, v131
	v_pk_fma_f32 v[74:75], v[2:3], v[130:131], v[114:115] op_sel_hi:[1,0,1]
	v_pk_fma_f32 v[78:79], v[4:5], v[130:131], v[116:117] op_sel_hi:[1,0,1]
	global_store_short v152, v132, s[100:101]
	v_pk_fma_f32 v[80:81], v[6:7], v[130:131], v[118:119] op_sel_hi:[1,0,1]
	v_pk_fma_f32 v[82:83], v[8:9], v[130:131], v[120:121] op_sel_hi:[1,0,1]
	v_pk_fma_f32 v[84:85], v[14:15], v[130:131], v[122:123] op_sel_hi:[1,0,1]
	v_pk_fma_f32 v[86:87], v[16:17], v[130:131], v[124:125] op_sel_hi:[1,0,1]
	v_pk_fma_f32 v[88:89], v[10:11], v[130:131], v[126:127] op_sel_hi:[1,0,1]
	v_pk_fma_f32 v[90:91], v[12:13], v[130:131], v[128:129] op_sel_hi:[1,0,1]
	s_waitcnt lgkmcnt(0)
	v_pk_mul_f32 v[114:115], v[70:71], v[74:75] op_sel_hi:[0,1]
	v_pk_mul_f32 v[116:117], v[70:71], v[78:79] op_sel_hi:[0,1]
	v_pk_fma_f32 v[110:111], v[114:115], v[50:51], 0 op_sel_hi:[1,1,0]
	v_pk_fma_f32 v[112:113], v[114:115], v[66:67], 0 op_sel_hi:[1,1,0]
	v_pk_mul_f32 v[118:119], v[70:71], v[80:81] op_sel_hi:[0,1]
	ds_read_b128 v[30:33], v94 offset:8000
	v_pk_fma_f32 v[110:111], v[116:117], v[52:53], v[110:111]
	v_pk_fma_f32 v[112:113], v[116:117], v[68:69], v[112:113]
	v_pk_mul_f32 v[120:121], v[70:71], v[82:83] op_sel_hi:[0,1]
	ds_read_b128 v[26:29], v94 offset:8016
	v_pk_fma_f32 v[110:111], v[118:119], v[46:47], v[110:111]
	v_pk_fma_f32 v[112:113], v[118:119], v[62:63], v[112:113]
	v_pk_mul_f32 v[122:123], v[70:71], v[84:85] op_sel_hi:[0,1]
	ds_read_b128 v[22:25], v94 offset:8032
	v_pk_fma_f32 v[110:111], v[120:121], v[48:49], v[110:111]
	v_pk_fma_f32 v[112:113], v[120:121], v[64:65], v[112:113]
	v_pk_mul_f32 v[124:125], v[70:71], v[86:87] op_sel_hi:[0,1]
	ds_read_b128 v[18:21], v94 offset:8048
	v_pk_fma_f32 v[110:111], v[122:123], v[42:43], v[110:111]
	v_pk_fma_f32 v[112:113], v[122:123], v[58:59], v[112:113]
	v_pk_mul_f32 v[126:127], v[70:71], v[88:89] op_sel_hi:[0,1]
	ds_read_b128 v[2:5], v94 offset:8256
	v_pk_fma_f32 v[110:111], v[124:125], v[44:45], v[110:111]
	v_pk_fma_f32 v[112:113], v[124:125], v[60:61], v[112:113]
	v_pk_mul_f32 v[128:129], v[70:71], v[90:91] op_sel_hi:[0,1]
	ds_read_b128 v[6:9], v94 offset:8272
	v_pk_fma_f32 v[110:111], v[126:127], v[38:39], v[110:111]
	v_pk_fma_f32 v[112:113], v[126:127], v[54:55], v[112:113]
	ds_read_b128 v[14:17], v94 offset:8288
	v_pk_fma_f32 v[110:111], v[128:129], v[40:41], v[110:111]
	v_pk_fma_f32 v[112:113], v[128:129], v[56:57], v[112:113]
	ds_read_b128 v[10:13], v94 offset:8304
	v_add_f32_e32 v134, v110, v111
	v_add_f32_e32 v135, v112, v113
	ds_read_b32 v73, v95 offset:8512
	v_add_f32_dpp v134, v134, v134 quad_perm:[1,0,3,2] row_mask:0xf bank_mask:0xf bound_ctrl:1
	v_add_f32_dpp v135, v135, v135 quad_perm:[1,0,3,2] row_mask:0xf bank_mask:0xf bound_ctrl:1
	ds_read_b96 v[34:36], v1 offset:8768
	v_add_f32_dpp v134, v134, v134 quad_perm:[2,3,0,1] row_mask:0xf bank_mask:0xf bound_ctrl:1
	v_add_f32_dpp v135, v135, v135 quad_perm:[2,3,0,1] row_mask:0xf bank_mask:0xf bound_ctrl:1
	v_sub_f32_e32 v134, v0, v134
	v_mul_f32_e32 v134, v71, v134
	v_fma_f32 v135, v72, v134, v135
	v_cvt_pk_bf16_f32 v133, v135, v135
	v_pk_fma_f32 v[74:75], v[50:51], v[134:135], v[114:115] op_sel_hi:[1,0,1]
	v_pk_fma_f32 v[78:79], v[52:53], v[134:135], v[116:117] op_sel_hi:[1,0,1]
	global_store_short v153, v133, s[100:101]
	v_pk_fma_f32 v[80:81], v[46:47], v[134:135], v[118:119] op_sel_hi:[1,0,1]
	v_pk_fma_f32 v[82:83], v[48:49], v[134:135], v[120:121] op_sel_hi:[1,0,1]
	v_pk_fma_f32 v[84:85], v[42:43], v[134:135], v[122:123] op_sel_hi:[1,0,1]
	v_pk_fma_f32 v[86:87], v[44:45], v[134:135], v[124:125] op_sel_hi:[1,0,1]
	v_pk_fma_f32 v[88:89], v[38:39], v[134:135], v[126:127] op_sel_hi:[1,0,1]
	v_pk_fma_f32 v[90:91], v[40:41], v[134:135], v[128:129] op_sel_hi:[1,0,1]
	s_waitcnt lgkmcnt(0)
	v_pk_mul_f32 v[114:115], v[34:35], v[74:75] op_sel_hi:[0,1]
	v_pk_mul_f32 v[116:117], v[34:35], v[78:79] op_sel_hi:[0,1]
	v_pk_fma_f32 v[106:107], v[114:115], v[2:3], 0 op_sel_hi:[1,1,0]
	v_pk_fma_f32 v[108:109], v[114:115], v[30:31], 0 op_sel_hi:[1,1,0]
	v_pk_mul_f32 v[118:119], v[34:35], v[80:81] op_sel_hi:[0,1]
	ds_read_b128 v[66:69], v94 offset:8800
	v_pk_fma_f32 v[106:107], v[116:117], v[4:5], v[106:107]
	v_pk_fma_f32 v[108:109], v[116:117], v[32:33], v[108:109]
	v_pk_mul_f32 v[120:121], v[34:35], v[82:83] op_sel_hi:[0,1]
	ds_read_b128 v[62:65], v94 offset:8816
	v_pk_fma_f32 v[106:107], v[118:119], v[6:7], v[106:107]
	v_pk_fma_f32 v[108:109], v[118:119], v[26:27], v[108:109]
	v_pk_mul_f32 v[122:123], v[34:35], v[84:85] op_sel_hi:[0,1]
	ds_read_b128 v[58:61], v94 offset:8832
	v_pk_fma_f32 v[106:107], v[120:121], v[8:9], v[106:107]
	v_pk_fma_f32 v[108:109], v[120:121], v[28:29], v[108:109]
	v_pk_mul_f32 v[124:125], v[34:35], v[86:87] op_sel_hi:[0,1]
	ds_read_b128 v[54:57], v94 offset:8848
	v_pk_fma_f32 v[106:107], v[122:123], v[14:15], v[106:107]
	v_pk_fma_f32 v[108:109], v[122:123], v[22:23], v[108:109]
	v_pk_mul_f32 v[126:127], v[34:35], v[88:89] op_sel_hi:[0,1]
	ds_read_b128 v[50:53], v94 offset:9056
	v_pk_fma_f32 v[106:107], v[124:125], v[16:17], v[106:107]
	v_pk_fma_f32 v[108:109], v[124:125], v[24:25], v[108:109]
	v_pk_mul_f32 v[128:129], v[34:35], v[90:91] op_sel_hi:[0,1]
	ds_read_b128 v[46:49], v94 offset:9072
	v_pk_fma_f32 v[106:107], v[126:127], v[10:11], v[106:107]
	v_pk_fma_f32 v[108:109], v[126:127], v[18:19], v[108:109]
	ds_read_b128 v[42:45], v94 offset:9088
	v_pk_fma_f32 v[106:107], v[128:129], v[12:13], v[106:107]
	v_pk_fma_f32 v[108:109], v[128:129], v[20:21], v[108:109]
	ds_read_b128 v[38:41], v94 offset:9104
	v_add_f32_e32 v130, v106, v107
	v_add_f32_e32 v131, v108, v109
	ds_read_b32 v0, v95 offset:9312
	v_add_f32_dpp v130, v130, v130 quad_perm:[1,0,3,2] row_mask:0xf bank_mask:0xf bound_ctrl:1
	v_add_f32_dpp v131, v131, v131 quad_perm:[1,0,3,2] row_mask:0xf bank_mask:0xf bound_ctrl:1
	ds_read_b96 v[70:72], v1 offset:9568
	v_add_f32_dpp v130, v130, v130 quad_perm:[2,3,0,1] row_mask:0xf bank_mask:0xf bound_ctrl:1
	v_add_f32_dpp v131, v131, v131 quad_perm:[2,3,0,1] row_mask:0xf bank_mask:0xf bound_ctrl:1
	v_sub_f32_e32 v130, v73, v130
	v_mul_f32_e32 v130, v35, v130
	v_fma_f32 v131, v36, v130, v131
	v_cvt_pk_bf16_f32 v132, v131, v131
	v_pk_fma_f32 v[74:75], v[2:3], v[130:131], v[114:115] op_sel_hi:[1,0,1]
	v_pk_fma_f32 v[78:79], v[4:5], v[130:131], v[116:117] op_sel_hi:[1,0,1]
	global_store_short v154, v132, s[100:101]
	v_pk_fma_f32 v[80:81], v[6:7], v[130:131], v[118:119] op_sel_hi:[1,0,1]
	v_pk_fma_f32 v[82:83], v[8:9], v[130:131], v[120:121] op_sel_hi:[1,0,1]
	v_pk_fma_f32 v[84:85], v[14:15], v[130:131], v[122:123] op_sel_hi:[1,0,1]
	v_pk_fma_f32 v[86:87], v[16:17], v[130:131], v[124:125] op_sel_hi:[1,0,1]
	v_pk_fma_f32 v[88:89], v[10:11], v[130:131], v[126:127] op_sel_hi:[1,0,1]
	v_pk_fma_f32 v[90:91], v[12:13], v[130:131], v[128:129] op_sel_hi:[1,0,1]
	s_waitcnt lgkmcnt(0)
	v_pk_mul_f32 v[114:115], v[70:71], v[74:75] op_sel_hi:[0,1]
	v_pk_mul_f32 v[116:117], v[70:71], v[78:79] op_sel_hi:[0,1]
	v_pk_fma_f32 v[110:111], v[114:115], v[50:51], 0 op_sel_hi:[1,1,0]
	v_pk_fma_f32 v[112:113], v[114:115], v[66:67], 0 op_sel_hi:[1,1,0]
	v_pk_mul_f32 v[118:119], v[70:71], v[80:81] op_sel_hi:[0,1]
	ds_read_b128 v[30:33], v94 offset:9600
	v_pk_fma_f32 v[110:111], v[116:117], v[52:53], v[110:111]
	v_pk_fma_f32 v[112:113], v[116:117], v[68:69], v[112:113]
	v_pk_mul_f32 v[120:121], v[70:71], v[82:83] op_sel_hi:[0,1]
	ds_read_b128 v[26:29], v94 offset:9616
	v_pk_fma_f32 v[110:111], v[118:119], v[46:47], v[110:111]
	v_pk_fma_f32 v[112:113], v[118:119], v[62:63], v[112:113]
	v_pk_mul_f32 v[122:123], v[70:71], v[84:85] op_sel_hi:[0,1]
	ds_read_b128 v[22:25], v94 offset:9632
	v_pk_fma_f32 v[110:111], v[120:121], v[48:49], v[110:111]
	v_pk_fma_f32 v[112:113], v[120:121], v[64:65], v[112:113]
	v_pk_mul_f32 v[124:125], v[70:71], v[86:87] op_sel_hi:[0,1]
	ds_read_b128 v[18:21], v94 offset:9648
	v_pk_fma_f32 v[110:111], v[122:123], v[42:43], v[110:111]
	v_pk_fma_f32 v[112:113], v[122:123], v[58:59], v[112:113]
	v_pk_mul_f32 v[126:127], v[70:71], v[88:89] op_sel_hi:[0,1]
	ds_read_b128 v[2:5], v94 offset:9856
	v_pk_fma_f32 v[110:111], v[124:125], v[44:45], v[110:111]
	v_pk_fma_f32 v[112:113], v[124:125], v[60:61], v[112:113]
	v_pk_mul_f32 v[128:129], v[70:71], v[90:91] op_sel_hi:[0,1]
	ds_read_b128 v[6:9], v94 offset:9872
	v_pk_fma_f32 v[110:111], v[126:127], v[38:39], v[110:111]
	v_pk_fma_f32 v[112:113], v[126:127], v[54:55], v[112:113]
	ds_read_b128 v[14:17], v94 offset:9888
	v_pk_fma_f32 v[110:111], v[128:129], v[40:41], v[110:111]
	v_pk_fma_f32 v[112:113], v[128:129], v[56:57], v[112:113]
	ds_read_b128 v[10:13], v94 offset:9904
	v_add_f32_e32 v134, v110, v111
	v_add_f32_e32 v135, v112, v113
	ds_read_b32 v73, v95 offset:10112
	v_add_f32_dpp v134, v134, v134 quad_perm:[1,0,3,2] row_mask:0xf bank_mask:0xf bound_ctrl:1
	v_add_f32_dpp v135, v135, v135 quad_perm:[1,0,3,2] row_mask:0xf bank_mask:0xf bound_ctrl:1
	ds_read_b96 v[34:36], v1 offset:10368
	v_add_f32_dpp v134, v134, v134 quad_perm:[2,3,0,1] row_mask:0xf bank_mask:0xf bound_ctrl:1
	v_add_f32_dpp v135, v135, v135 quad_perm:[2,3,0,1] row_mask:0xf bank_mask:0xf bound_ctrl:1
	v_sub_f32_e32 v134, v0, v134
	v_mul_f32_e32 v134, v71, v134
	v_fma_f32 v135, v72, v134, v135
	v_cvt_pk_bf16_f32 v133, v135, v135
	v_pk_fma_f32 v[74:75], v[50:51], v[134:135], v[114:115] op_sel_hi:[1,0,1]
	v_pk_fma_f32 v[78:79], v[52:53], v[134:135], v[116:117] op_sel_hi:[1,0,1]
	global_store_short v155, v133, s[100:101]
	v_pk_fma_f32 v[80:81], v[46:47], v[134:135], v[118:119] op_sel_hi:[1,0,1]
	v_pk_fma_f32 v[82:83], v[48:49], v[134:135], v[120:121] op_sel_hi:[1,0,1]
	v_pk_fma_f32 v[84:85], v[42:43], v[134:135], v[122:123] op_sel_hi:[1,0,1]
	v_pk_fma_f32 v[86:87], v[44:45], v[134:135], v[124:125] op_sel_hi:[1,0,1]
	v_pk_fma_f32 v[88:89], v[38:39], v[134:135], v[126:127] op_sel_hi:[1,0,1]
	v_pk_fma_f32 v[90:91], v[40:41], v[134:135], v[128:129] op_sel_hi:[1,0,1]
	s_waitcnt lgkmcnt(0)
	v_pk_mul_f32 v[114:115], v[34:35], v[74:75] op_sel_hi:[0,1]
	v_pk_mul_f32 v[116:117], v[34:35], v[78:79] op_sel_hi:[0,1]
	v_pk_fma_f32 v[106:107], v[114:115], v[2:3], 0 op_sel_hi:[1,1,0]
	v_pk_fma_f32 v[108:109], v[114:115], v[30:31], 0 op_sel_hi:[1,1,0]
	v_pk_mul_f32 v[118:119], v[34:35], v[80:81] op_sel_hi:[0,1]
	ds_read_b128 v[66:69], v94 offset:10400
	v_pk_fma_f32 v[106:107], v[116:117], v[4:5], v[106:107]
	v_pk_fma_f32 v[108:109], v[116:117], v[32:33], v[108:109]
	v_pk_mul_f32 v[120:121], v[34:35], v[82:83] op_sel_hi:[0,1]
	ds_read_b128 v[62:65], v94 offset:10416
	v_pk_fma_f32 v[106:107], v[118:119], v[6:7], v[106:107]
	v_pk_fma_f32 v[108:109], v[118:119], v[26:27], v[108:109]
	v_pk_mul_f32 v[122:123], v[34:35], v[84:85] op_sel_hi:[0,1]
	ds_read_b128 v[58:61], v94 offset:10432
	v_pk_fma_f32 v[106:107], v[120:121], v[8:9], v[106:107]
	v_pk_fma_f32 v[108:109], v[120:121], v[28:29], v[108:109]
	v_pk_mul_f32 v[124:125], v[34:35], v[86:87] op_sel_hi:[0,1]
	ds_read_b128 v[54:57], v94 offset:10448
	v_pk_fma_f32 v[106:107], v[122:123], v[14:15], v[106:107]
	v_pk_fma_f32 v[108:109], v[122:123], v[22:23], v[108:109]
	v_pk_mul_f32 v[126:127], v[34:35], v[88:89] op_sel_hi:[0,1]
	ds_read_b128 v[50:53], v94 offset:10656
	v_pk_fma_f32 v[106:107], v[124:125], v[16:17], v[106:107]
	v_pk_fma_f32 v[108:109], v[124:125], v[24:25], v[108:109]
	v_pk_mul_f32 v[128:129], v[34:35], v[90:91] op_sel_hi:[0,1]
	ds_read_b128 v[46:49], v94 offset:10672
	v_pk_fma_f32 v[106:107], v[126:127], v[10:11], v[106:107]
	v_pk_fma_f32 v[108:109], v[126:127], v[18:19], v[108:109]
	ds_read_b128 v[42:45], v94 offset:10688
	v_pk_fma_f32 v[106:107], v[128:129], v[12:13], v[106:107]
	v_pk_fma_f32 v[108:109], v[128:129], v[20:21], v[108:109]
	ds_read_b128 v[38:41], v94 offset:10704
	v_add_f32_e32 v130, v106, v107
	v_add_f32_e32 v131, v108, v109
	ds_read_b32 v0, v95 offset:10912
	v_add_f32_dpp v130, v130, v130 quad_perm:[1,0,3,2] row_mask:0xf bank_mask:0xf bound_ctrl:1
	v_add_f32_dpp v131, v131, v131 quad_perm:[1,0,3,2] row_mask:0xf bank_mask:0xf bound_ctrl:1
	ds_read_b96 v[70:72], v1 offset:11168
	v_add_f32_dpp v130, v130, v130 quad_perm:[2,3,0,1] row_mask:0xf bank_mask:0xf bound_ctrl:1
	v_add_f32_dpp v131, v131, v131 quad_perm:[2,3,0,1] row_mask:0xf bank_mask:0xf bound_ctrl:1
	v_sub_f32_e32 v130, v73, v130
	v_mul_f32_e32 v130, v35, v130
	v_fma_f32 v131, v36, v130, v131
	v_cvt_pk_bf16_f32 v132, v131, v131
	v_pk_fma_f32 v[74:75], v[2:3], v[130:131], v[114:115] op_sel_hi:[1,0,1]
	v_pk_fma_f32 v[78:79], v[4:5], v[130:131], v[116:117] op_sel_hi:[1,0,1]
	global_store_short v156, v132, s[100:101]
	v_pk_fma_f32 v[80:81], v[6:7], v[130:131], v[118:119] op_sel_hi:[1,0,1]
	v_pk_fma_f32 v[82:83], v[8:9], v[130:131], v[120:121] op_sel_hi:[1,0,1]
	v_pk_fma_f32 v[84:85], v[14:15], v[130:131], v[122:123] op_sel_hi:[1,0,1]
	v_pk_fma_f32 v[86:87], v[16:17], v[130:131], v[124:125] op_sel_hi:[1,0,1]
	v_pk_fma_f32 v[88:89], v[10:11], v[130:131], v[126:127] op_sel_hi:[1,0,1]
	v_pk_fma_f32 v[90:91], v[12:13], v[130:131], v[128:129] op_sel_hi:[1,0,1]
	s_waitcnt lgkmcnt(0)
	v_pk_mul_f32 v[114:115], v[70:71], v[74:75] op_sel_hi:[0,1]
	v_pk_mul_f32 v[116:117], v[70:71], v[78:79] op_sel_hi:[0,1]
	v_pk_fma_f32 v[110:111], v[114:115], v[50:51], 0 op_sel_hi:[1,1,0]
	v_pk_fma_f32 v[112:113], v[114:115], v[66:67], 0 op_sel_hi:[1,1,0]
	v_pk_mul_f32 v[118:119], v[70:71], v[80:81] op_sel_hi:[0,1]
	ds_read_b128 v[30:33], v94 offset:11200
	v_pk_fma_f32 v[110:111], v[116:117], v[52:53], v[110:111]
	v_pk_fma_f32 v[112:113], v[116:117], v[68:69], v[112:113]
	v_pk_mul_f32 v[120:121], v[70:71], v[82:83] op_sel_hi:[0,1]
	ds_read_b128 v[26:29], v94 offset:11216
	v_pk_fma_f32 v[110:111], v[118:119], v[46:47], v[110:111]
	v_pk_fma_f32 v[112:113], v[118:119], v[62:63], v[112:113]
	v_pk_mul_f32 v[122:123], v[70:71], v[84:85] op_sel_hi:[0,1]
	ds_read_b128 v[22:25], v94 offset:11232
	v_pk_fma_f32 v[110:111], v[120:121], v[48:49], v[110:111]
	v_pk_fma_f32 v[112:113], v[120:121], v[64:65], v[112:113]
	v_pk_mul_f32 v[124:125], v[70:71], v[86:87] op_sel_hi:[0,1]
	ds_read_b128 v[18:21], v94 offset:11248
	v_pk_fma_f32 v[110:111], v[122:123], v[42:43], v[110:111]
	v_pk_fma_f32 v[112:113], v[122:123], v[58:59], v[112:113]
	v_pk_mul_f32 v[126:127], v[70:71], v[88:89] op_sel_hi:[0,1]
	ds_read_b128 v[2:5], v94 offset:11456
	v_pk_fma_f32 v[110:111], v[124:125], v[44:45], v[110:111]
	v_pk_fma_f32 v[112:113], v[124:125], v[60:61], v[112:113]
	v_pk_mul_f32 v[128:129], v[70:71], v[90:91] op_sel_hi:[0,1]
	ds_read_b128 v[6:9], v94 offset:11472
	v_pk_fma_f32 v[110:111], v[126:127], v[38:39], v[110:111]
	v_pk_fma_f32 v[112:113], v[126:127], v[54:55], v[112:113]
	ds_read_b128 v[14:17], v94 offset:11488
	v_pk_fma_f32 v[110:111], v[128:129], v[40:41], v[110:111]
	v_pk_fma_f32 v[112:113], v[128:129], v[56:57], v[112:113]
	ds_read_b128 v[10:13], v94 offset:11504
	v_add_f32_e32 v134, v110, v111
	v_add_f32_e32 v135, v112, v113
	ds_read_b32 v73, v95 offset:11712
	v_add_f32_dpp v134, v134, v134 quad_perm:[1,0,3,2] row_mask:0xf bank_mask:0xf bound_ctrl:1
	v_add_f32_dpp v135, v135, v135 quad_perm:[1,0,3,2] row_mask:0xf bank_mask:0xf bound_ctrl:1
	ds_read_b96 v[34:36], v1 offset:11968
	v_add_f32_dpp v134, v134, v134 quad_perm:[2,3,0,1] row_mask:0xf bank_mask:0xf bound_ctrl:1
	v_add_f32_dpp v135, v135, v135 quad_perm:[2,3,0,1] row_mask:0xf bank_mask:0xf bound_ctrl:1
	v_sub_f32_e32 v134, v0, v134
	v_mul_f32_e32 v134, v71, v134
	v_fma_f32 v135, v72, v134, v135
	v_cvt_pk_bf16_f32 v133, v135, v135
	v_pk_fma_f32 v[74:75], v[50:51], v[134:135], v[114:115] op_sel_hi:[1,0,1]
	v_pk_fma_f32 v[78:79], v[52:53], v[134:135], v[116:117] op_sel_hi:[1,0,1]
	global_store_short v157, v133, s[100:101]
	v_pk_fma_f32 v[80:81], v[46:47], v[134:135], v[118:119] op_sel_hi:[1,0,1]
	v_pk_fma_f32 v[82:83], v[48:49], v[134:135], v[120:121] op_sel_hi:[1,0,1]
	v_pk_fma_f32 v[84:85], v[42:43], v[134:135], v[122:123] op_sel_hi:[1,0,1]
	v_pk_fma_f32 v[86:87], v[44:45], v[134:135], v[124:125] op_sel_hi:[1,0,1]
	v_pk_fma_f32 v[88:89], v[38:39], v[134:135], v[126:127] op_sel_hi:[1,0,1]
	v_pk_fma_f32 v[90:91], v[40:41], v[134:135], v[128:129] op_sel_hi:[1,0,1]
	s_waitcnt lgkmcnt(0)
	v_pk_mul_f32 v[114:115], v[34:35], v[74:75] op_sel_hi:[0,1]
	v_pk_mul_f32 v[116:117], v[34:35], v[78:79] op_sel_hi:[0,1]
	v_pk_fma_f32 v[106:107], v[114:115], v[2:3], 0 op_sel_hi:[1,1,0]
	v_pk_fma_f32 v[108:109], v[114:115], v[30:31], 0 op_sel_hi:[1,1,0]
	v_pk_mul_f32 v[118:119], v[34:35], v[80:81] op_sel_hi:[0,1]
	ds_read_b128 v[66:69], v94 offset:12000
	v_pk_fma_f32 v[106:107], v[116:117], v[4:5], v[106:107]
	v_pk_fma_f32 v[108:109], v[116:117], v[32:33], v[108:109]
	v_pk_mul_f32 v[120:121], v[34:35], v[82:83] op_sel_hi:[0,1]
	ds_read_b128 v[62:65], v94 offset:12016
	v_pk_fma_f32 v[106:107], v[118:119], v[6:7], v[106:107]
	v_pk_fma_f32 v[108:109], v[118:119], v[26:27], v[108:109]
	v_pk_mul_f32 v[122:123], v[34:35], v[84:85] op_sel_hi:[0,1]
	ds_read_b128 v[58:61], v94 offset:12032
	v_pk_fma_f32 v[106:107], v[120:121], v[8:9], v[106:107]
	v_pk_fma_f32 v[108:109], v[120:121], v[28:29], v[108:109]
	v_pk_mul_f32 v[124:125], v[34:35], v[86:87] op_sel_hi:[0,1]
	ds_read_b128 v[54:57], v94 offset:12048
	v_pk_fma_f32 v[106:107], v[122:123], v[14:15], v[106:107]
	v_pk_fma_f32 v[108:109], v[122:123], v[22:23], v[108:109]
	v_pk_mul_f32 v[126:127], v[34:35], v[88:89] op_sel_hi:[0,1]
	ds_read_b128 v[50:53], v94 offset:12256
	v_pk_fma_f32 v[106:107], v[124:125], v[16:17], v[106:107]
	v_pk_fma_f32 v[108:109], v[124:125], v[24:25], v[108:109]
	v_pk_mul_f32 v[128:129], v[34:35], v[90:91] op_sel_hi:[0,1]
	ds_read_b128 v[46:49], v94 offset:12272
	v_pk_fma_f32 v[106:107], v[126:127], v[10:11], v[106:107]
	v_pk_fma_f32 v[108:109], v[126:127], v[18:19], v[108:109]
	ds_read_b128 v[42:45], v94 offset:12288
	v_pk_fma_f32 v[106:107], v[128:129], v[12:13], v[106:107]
	v_pk_fma_f32 v[108:109], v[128:129], v[20:21], v[108:109]
	ds_read_b128 v[38:41], v94 offset:12304
	v_add_f32_e32 v130, v106, v107
	v_add_f32_e32 v131, v108, v109
	ds_read_b32 v0, v95 offset:12512
	v_add_f32_dpp v130, v130, v130 quad_perm:[1,0,3,2] row_mask:0xf bank_mask:0xf bound_ctrl:1
	v_add_f32_dpp v131, v131, v131 quad_perm:[1,0,3,2] row_mask:0xf bank_mask:0xf bound_ctrl:1
	ds_read_b96 v[70:72], v1 offset:12768
	v_add_f32_dpp v130, v130, v130 quad_perm:[2,3,0,1] row_mask:0xf bank_mask:0xf bound_ctrl:1
	v_add_f32_dpp v131, v131, v131 quad_perm:[2,3,0,1] row_mask:0xf bank_mask:0xf bound_ctrl:1
	v_sub_f32_e32 v130, v73, v130
	v_mul_f32_e32 v130, v35, v130
	v_fma_f32 v131, v36, v130, v131
	v_cvt_pk_bf16_f32 v132, v131, v131
	v_pk_fma_f32 v[74:75], v[2:3], v[130:131], v[114:115] op_sel_hi:[1,0,1]
	v_pk_fma_f32 v[78:79], v[4:5], v[130:131], v[116:117] op_sel_hi:[1,0,1]
	global_store_short v158, v132, s[100:101]
	v_pk_fma_f32 v[80:81], v[6:7], v[130:131], v[118:119] op_sel_hi:[1,0,1]
	v_pk_fma_f32 v[82:83], v[8:9], v[130:131], v[120:121] op_sel_hi:[1,0,1]
	v_pk_fma_f32 v[84:85], v[14:15], v[130:131], v[122:123] op_sel_hi:[1,0,1]
	v_pk_fma_f32 v[86:87], v[16:17], v[130:131], v[124:125] op_sel_hi:[1,0,1]
	v_pk_fma_f32 v[88:89], v[10:11], v[130:131], v[126:127] op_sel_hi:[1,0,1]
	v_pk_fma_f32 v[90:91], v[12:13], v[130:131], v[128:129] op_sel_hi:[1,0,1]
	s_waitcnt lgkmcnt(0)
	v_pk_mul_f32 v[114:115], v[70:71], v[74:75] op_sel_hi:[0,1]
	v_pk_mul_f32 v[116:117], v[70:71], v[78:79] op_sel_hi:[0,1]
	v_pk_fma_f32 v[110:111], v[114:115], v[50:51], 0 op_sel_hi:[1,1,0]
	v_pk_fma_f32 v[112:113], v[114:115], v[66:67], 0 op_sel_hi:[1,1,0]
	v_pk_mul_f32 v[118:119], v[70:71], v[80:81] op_sel_hi:[0,1]
	ds_read_b128 v[30:33], v94 offset:12800
	v_pk_fma_f32 v[110:111], v[116:117], v[52:53], v[110:111]
	v_pk_fma_f32 v[112:113], v[116:117], v[68:69], v[112:113]
	v_pk_mul_f32 v[120:121], v[70:71], v[82:83] op_sel_hi:[0,1]
	ds_read_b128 v[26:29], v94 offset:12816
	v_pk_fma_f32 v[110:111], v[118:119], v[46:47], v[110:111]
	v_pk_fma_f32 v[112:113], v[118:119], v[62:63], v[112:113]
	v_pk_mul_f32 v[122:123], v[70:71], v[84:85] op_sel_hi:[0,1]
	ds_read_b128 v[22:25], v94 offset:12832
	v_pk_fma_f32 v[110:111], v[120:121], v[48:49], v[110:111]
	v_pk_fma_f32 v[112:113], v[120:121], v[64:65], v[112:113]
	v_pk_mul_f32 v[124:125], v[70:71], v[86:87] op_sel_hi:[0,1]
	ds_read_b128 v[18:21], v94 offset:12848
	v_pk_fma_f32 v[110:111], v[122:123], v[42:43], v[110:111]
	v_pk_fma_f32 v[112:113], v[122:123], v[58:59], v[112:113]
	v_pk_mul_f32 v[126:127], v[70:71], v[88:89] op_sel_hi:[0,1]
	ds_read_b128 v[2:5], v94 offset:13056
	v_pk_fma_f32 v[110:111], v[124:125], v[44:45], v[110:111]
	v_pk_fma_f32 v[112:113], v[124:125], v[60:61], v[112:113]
	v_pk_mul_f32 v[128:129], v[70:71], v[90:91] op_sel_hi:[0,1]
	ds_read_b128 v[6:9], v94 offset:13072
	v_pk_fma_f32 v[110:111], v[126:127], v[38:39], v[110:111]
	v_pk_fma_f32 v[112:113], v[126:127], v[54:55], v[112:113]
	ds_read_b128 v[14:17], v94 offset:13088
	v_pk_fma_f32 v[110:111], v[128:129], v[40:41], v[110:111]
	v_pk_fma_f32 v[112:113], v[128:129], v[56:57], v[112:113]
	ds_read_b128 v[10:13], v94 offset:13104
	v_add_f32_e32 v134, v110, v111
	v_add_f32_e32 v135, v112, v113
	ds_read_b32 v73, v95 offset:13312
	v_add_f32_dpp v134, v134, v134 quad_perm:[1,0,3,2] row_mask:0xf bank_mask:0xf bound_ctrl:1
	v_add_f32_dpp v135, v135, v135 quad_perm:[1,0,3,2] row_mask:0xf bank_mask:0xf bound_ctrl:1
	ds_read_b96 v[34:36], v1 offset:13568
	v_add_f32_dpp v134, v134, v134 quad_perm:[2,3,0,1] row_mask:0xf bank_mask:0xf bound_ctrl:1
	v_add_f32_dpp v135, v135, v135 quad_perm:[2,3,0,1] row_mask:0xf bank_mask:0xf bound_ctrl:1
	v_sub_f32_e32 v134, v0, v134
	v_mul_f32_e32 v134, v71, v134
	v_fma_f32 v135, v72, v134, v135
	v_cvt_pk_bf16_f32 v133, v135, v135
	v_pk_fma_f32 v[74:75], v[50:51], v[134:135], v[114:115] op_sel_hi:[1,0,1]
	v_pk_fma_f32 v[78:79], v[52:53], v[134:135], v[116:117] op_sel_hi:[1,0,1]
	global_store_short v159, v133, s[100:101]
	v_pk_fma_f32 v[80:81], v[46:47], v[134:135], v[118:119] op_sel_hi:[1,0,1]
	v_pk_fma_f32 v[82:83], v[48:49], v[134:135], v[120:121] op_sel_hi:[1,0,1]
	v_pk_fma_f32 v[84:85], v[42:43], v[134:135], v[122:123] op_sel_hi:[1,0,1]
	v_pk_fma_f32 v[86:87], v[44:45], v[134:135], v[124:125] op_sel_hi:[1,0,1]
	v_pk_fma_f32 v[88:89], v[38:39], v[134:135], v[126:127] op_sel_hi:[1,0,1]
	v_pk_fma_f32 v[90:91], v[40:41], v[134:135], v[128:129] op_sel_hi:[1,0,1]

.LBB0_916:
	v_readfirstlane_b32 s100, v92
	v_readfirstlane_b32 s101, v93
	s_sub_u32 s100, s100, m0
	s_subb_u32 s101, s101, 0
	s_waitcnt lgkmcnt(0)
	v_pk_mul_f32 v[114:115], v[34:35], v[74:75] op_sel_hi:[0,1]
	v_pk_mul_f32 v[116:117], v[34:35], v[78:79] op_sel_hi:[0,1]
	v_pk_fma_f32 v[106:107], v[114:115], v[2:3], 0 op_sel_hi:[1,1,0]
	v_pk_fma_f32 v[108:109], v[114:115], v[30:31], 0 op_sel_hi:[1,1,0]
	v_pk_mul_f32 v[118:119], v[34:35], v[80:81] op_sel_hi:[0,1]
	ds_read_b128 v[66:69], v94 offset:13600
	v_pk_fma_f32 v[106:107], v[116:117], v[4:5], v[106:107]
	v_pk_fma_f32 v[108:109], v[116:117], v[32:33], v[108:109]
	v_pk_mul_f32 v[120:121], v[34:35], v[82:83] op_sel_hi:[0,1]
	ds_read_b128 v[62:65], v94 offset:13616
	v_pk_fma_f32 v[106:107], v[118:119], v[6:7], v[106:107]
	v_pk_fma_f32 v[108:109], v[118:119], v[26:27], v[108:109]
	v_pk_mul_f32 v[122:123], v[34:35], v[84:85] op_sel_hi:[0,1]
	ds_read_b128 v[58:61], v94 offset:13632
	v_pk_fma_f32 v[106:107], v[120:121], v[8:9], v[106:107]
	v_pk_fma_f32 v[108:109], v[120:121], v[28:29], v[108:109]
	v_pk_mul_f32 v[124:125], v[34:35], v[86:87] op_sel_hi:[0,1]
	ds_read_b128 v[54:57], v94 offset:13648
	v_pk_fma_f32 v[106:107], v[122:123], v[14:15], v[106:107]
	v_pk_fma_f32 v[108:109], v[122:123], v[22:23], v[108:109]
	v_pk_mul_f32 v[126:127], v[34:35], v[88:89] op_sel_hi:[0,1]
	ds_read_b128 v[50:53], v94 offset:13856
	v_pk_fma_f32 v[106:107], v[124:125], v[16:17], v[106:107]
	v_pk_fma_f32 v[108:109], v[124:125], v[24:25], v[108:109]
	v_pk_mul_f32 v[128:129], v[34:35], v[90:91] op_sel_hi:[0,1]
	ds_read_b128 v[46:49], v94 offset:13872
	v_pk_fma_f32 v[106:107], v[126:127], v[10:11], v[106:107]
	v_pk_fma_f32 v[108:109], v[126:127], v[18:19], v[108:109]
	ds_read_b128 v[42:45], v94 offset:13888
	v_pk_fma_f32 v[106:107], v[128:129], v[12:13], v[106:107]
	v_pk_fma_f32 v[108:109], v[128:129], v[20:21], v[108:109]
	ds_read_b128 v[38:41], v94 offset:13904
	v_add_f32_e32 v130, v106, v107
	v_add_f32_e32 v131, v108, v109
	ds_read_b32 v0, v95 offset:14112
	v_add_f32_dpp v130, v130, v130 quad_perm:[1,0,3,2] row_mask:0xf bank_mask:0xf bound_ctrl:1
	v_add_f32_dpp v131, v131, v131 quad_perm:[1,0,3,2] row_mask:0xf bank_mask:0xf bound_ctrl:1
	ds_read_b96 v[70:72], v1 offset:14368
	v_add_f32_dpp v130, v130, v130 quad_perm:[2,3,0,1] row_mask:0xf bank_mask:0xf bound_ctrl:1
	v_add_f32_dpp v131, v131, v131 quad_perm:[2,3,0,1] row_mask:0xf bank_mask:0xf bound_ctrl:1
	v_sub_f32_e32 v130, v73, v130
	v_mul_f32_e32 v130, v35, v130
	v_fma_f32 v131, v36, v130, v131
	v_cvt_pk_bf16_f32 v132, v131, v131
	v_pk_fma_f32 v[74:75], v[2:3], v[130:131], v[114:115] op_sel_hi:[1,0,1]
	v_pk_fma_f32 v[78:79], v[4:5], v[130:131], v[116:117] op_sel_hi:[1,0,1]
	global_store_short v144, v132, s[100:101]
	v_pk_fma_f32 v[80:81], v[6:7], v[130:131], v[118:119] op_sel_hi:[1,0,1]
	v_pk_fma_f32 v[82:83], v[8:9], v[130:131], v[120:121] op_sel_hi:[1,0,1]
	v_pk_fma_f32 v[84:85], v[14:15], v[130:131], v[122:123] op_sel_hi:[1,0,1]
	v_pk_fma_f32 v[86:87], v[16:17], v[130:131], v[124:125] op_sel_hi:[1,0,1]
	v_pk_fma_f32 v[88:89], v[10:11], v[130:131], v[126:127] op_sel_hi:[1,0,1]
	v_pk_fma_f32 v[90:91], v[12:13], v[130:131], v[128:129] op_sel_hi:[1,0,1]
	s_waitcnt lgkmcnt(0)
	v_pk_mul_f32 v[114:115], v[70:71], v[74:75] op_sel_hi:[0,1]
	v_pk_mul_f32 v[116:117], v[70:71], v[78:79] op_sel_hi:[0,1]
	v_pk_fma_f32 v[110:111], v[114:115], v[50:51], 0 op_sel_hi:[1,1,0]
	v_pk_fma_f32 v[112:113], v[114:115], v[66:67], 0 op_sel_hi:[1,1,0]
	v_pk_mul_f32 v[118:119], v[70:71], v[80:81] op_sel_hi:[0,1]
	ds_read_b128 v[30:33], v94 offset:14400
	v_pk_fma_f32 v[110:111], v[116:117], v[52:53], v[110:111]
	v_pk_fma_f32 v[112:113], v[116:117], v[68:69], v[112:113]
	v_pk_mul_f32 v[120:121], v[70:71], v[82:83] op_sel_hi:[0,1]
	ds_read_b128 v[26:29], v94 offset:14416
	v_pk_fma_f32 v[110:111], v[118:119], v[46:47], v[110:111]
	v_pk_fma_f32 v[112:113], v[118:119], v[62:63], v[112:113]
	v_pk_mul_f32 v[122:123], v[70:71], v[84:85] op_sel_hi:[0,1]
	ds_read_b128 v[22:25], v94 offset:14432
	v_pk_fma_f32 v[110:111], v[120:121], v[48:49], v[110:111]
	v_pk_fma_f32 v[112:113], v[120:121], v[64:65], v[112:113]
	v_pk_mul_f32 v[124:125], v[70:71], v[86:87] op_sel_hi:[0,1]
	ds_read_b128 v[18:21], v94 offset:14448
	v_pk_fma_f32 v[110:111], v[122:123], v[42:43], v[110:111]
	v_pk_fma_f32 v[112:113], v[122:123], v[58:59], v[112:113]
	v_pk_mul_f32 v[126:127], v[70:71], v[88:89] op_sel_hi:[0,1]
	ds_read_b128 v[2:5], v94 offset:14656
	v_pk_fma_f32 v[110:111], v[124:125], v[44:45], v[110:111]
	v_pk_fma_f32 v[112:113], v[124:125], v[60:61], v[112:113]
	v_pk_mul_f32 v[128:129], v[70:71], v[90:91] op_sel_hi:[0,1]
	ds_read_b128 v[6:9], v94 offset:14672
	v_pk_fma_f32 v[110:111], v[126:127], v[38:39], v[110:111]
	v_pk_fma_f32 v[112:113], v[126:127], v[54:55], v[112:113]
	ds_read_b128 v[14:17], v94 offset:14688
	v_pk_fma_f32 v[110:111], v[128:129], v[40:41], v[110:111]
	v_pk_fma_f32 v[112:113], v[128:129], v[56:57], v[112:113]
	ds_read_b128 v[10:13], v94 offset:14704
	v_add_f32_e32 v134, v110, v111
	v_add_f32_e32 v135, v112, v113
	ds_read_b32 v73, v95 offset:14912
	v_add_f32_dpp v134, v134, v134 quad_perm:[1,0,3,2] row_mask:0xf bank_mask:0xf bound_ctrl:1
	v_add_f32_dpp v135, v135, v135 quad_perm:[1,0,3,2] row_mask:0xf bank_mask:0xf bound_ctrl:1
	ds_read_b96 v[34:36], v1 offset:15168
	v_add_f32_dpp v134, v134, v134 quad_perm:[2,3,0,1] row_mask:0xf bank_mask:0xf bound_ctrl:1
	v_add_f32_dpp v135, v135, v135 quad_perm:[2,3,0,1] row_mask:0xf bank_mask:0xf bound_ctrl:1
	v_sub_f32_e32 v134, v0, v134
	v_mul_f32_e32 v134, v71, v134
	v_fma_f32 v135, v72, v134, v135
	v_cvt_pk_bf16_f32 v133, v135, v135
	v_pk_fma_f32 v[74:75], v[50:51], v[134:135], v[114:115] op_sel_hi:[1,0,1]
	v_pk_fma_f32 v[78:79], v[52:53], v[134:135], v[116:117] op_sel_hi:[1,0,1]
	global_store_short v145, v133, s[100:101]
	v_pk_fma_f32 v[80:81], v[46:47], v[134:135], v[118:119] op_sel_hi:[1,0,1]
	v_pk_fma_f32 v[82:83], v[48:49], v[134:135], v[120:121] op_sel_hi:[1,0,1]
	v_pk_fma_f32 v[84:85], v[42:43], v[134:135], v[122:123] op_sel_hi:[1,0,1]
	v_pk_fma_f32 v[86:87], v[44:45], v[134:135], v[124:125] op_sel_hi:[1,0,1]
	v_pk_fma_f32 v[88:89], v[38:39], v[134:135], v[126:127] op_sel_hi:[1,0,1]
	v_pk_fma_f32 v[90:91], v[40:41], v[134:135], v[128:129] op_sel_hi:[1,0,1]
	s_waitcnt lgkmcnt(0)
	v_pk_mul_f32 v[114:115], v[34:35], v[74:75] op_sel_hi:[0,1]
	v_pk_mul_f32 v[116:117], v[34:35], v[78:79] op_sel_hi:[0,1]
	v_pk_fma_f32 v[106:107], v[114:115], v[2:3], 0 op_sel_hi:[1,1,0]
	v_pk_fma_f32 v[108:109], v[114:115], v[30:31], 0 op_sel_hi:[1,1,0]
	v_pk_mul_f32 v[118:119], v[34:35], v[80:81] op_sel_hi:[0,1]
	ds_read_b128 v[66:69], v94 offset:15200
	v_pk_fma_f32 v[106:107], v[116:117], v[4:5], v[106:107]
	v_pk_fma_f32 v[108:109], v[116:117], v[32:33], v[108:109]
	v_pk_mul_f32 v[120:121], v[34:35], v[82:83] op_sel_hi:[0,1]
	ds_read_b128 v[62:65], v94 offset:15216
	v_pk_fma_f32 v[106:107], v[118:119], v[6:7], v[106:107]
	v_pk_fma_f32 v[108:109], v[118:119], v[26:27], v[108:109]
	v_pk_mul_f32 v[122:123], v[34:35], v[84:85] op_sel_hi:[0,1]
	ds_read_b128 v[58:61], v94 offset:15232
	v_pk_fma_f32 v[106:107], v[120:121], v[8:9], v[106:107]
	v_pk_fma_f32 v[108:109], v[120:121], v[28:29], v[108:109]
	v_pk_mul_f32 v[124:125], v[34:35], v[86:87] op_sel_hi:[0,1]
	ds_read_b128 v[54:57], v94 offset:15248
	v_pk_fma_f32 v[106:107], v[122:123], v[14:15], v[106:107]
	v_pk_fma_f32 v[108:109], v[122:123], v[22:23], v[108:109]
	v_pk_mul_f32 v[126:127], v[34:35], v[88:89] op_sel_hi:[0,1]
	ds_read_b128 v[50:53], v94 offset:15456
	v_pk_fma_f32 v[106:107], v[124:125], v[16:17], v[106:107]
	v_pk_fma_f32 v[108:109], v[124:125], v[24:25], v[108:109]
	v_pk_mul_f32 v[128:129], v[34:35], v[90:91] op_sel_hi:[0,1]
	ds_read_b128 v[46:49], v94 offset:15472
	v_pk_fma_f32 v[106:107], v[126:127], v[10:11], v[106:107]
	v_pk_fma_f32 v[108:109], v[126:127], v[18:19], v[108:109]
	ds_read_b128 v[42:45], v94 offset:15488
	v_pk_fma_f32 v[106:107], v[128:129], v[12:13], v[106:107]
	v_pk_fma_f32 v[108:109], v[128:129], v[20:21], v[108:109]
	ds_read_b128 v[38:41], v94 offset:15504
	v_add_f32_e32 v130, v106, v107
	v_add_f32_e32 v131, v108, v109
	ds_read_b32 v0, v95 offset:15712
	v_add_f32_dpp v130, v130, v130 quad_perm:[1,0,3,2] row_mask:0xf bank_mask:0xf bound_ctrl:1
	v_add_f32_dpp v131, v131, v131 quad_perm:[1,0,3,2] row_mask:0xf bank_mask:0xf bound_ctrl:1
	ds_read_b96 v[70:72], v1 offset:15968
	v_add_f32_dpp v130, v130, v130 quad_perm:[2,3,0,1] row_mask:0xf bank_mask:0xf bound_ctrl:1
	v_add_f32_dpp v131, v131, v131 quad_perm:[2,3,0,1] row_mask:0xf bank_mask:0xf bound_ctrl:1
	v_sub_f32_e32 v130, v73, v130
	v_mul_f32_e32 v130, v35, v130
	v_fma_f32 v131, v36, v130, v131
	v_cvt_pk_bf16_f32 v132, v131, v131
	v_pk_fma_f32 v[74:75], v[2:3], v[130:131], v[114:115] op_sel_hi:[1,0,1]
	v_pk_fma_f32 v[78:79], v[4:5], v[130:131], v[116:117] op_sel_hi:[1,0,1]
	global_store_short v146, v132, s[100:101]
	v_pk_fma_f32 v[80:81], v[6:7], v[130:131], v[118:119] op_sel_hi:[1,0,1]
	v_pk_fma_f32 v[82:83], v[8:9], v[130:131], v[120:121] op_sel_hi:[1,0,1]
	v_pk_fma_f32 v[84:85], v[14:15], v[130:131], v[122:123] op_sel_hi:[1,0,1]
	v_pk_fma_f32 v[86:87], v[16:17], v[130:131], v[124:125] op_sel_hi:[1,0,1]
	v_pk_fma_f32 v[88:89], v[10:11], v[130:131], v[126:127] op_sel_hi:[1,0,1]
	v_pk_fma_f32 v[90:91], v[12:13], v[130:131], v[128:129] op_sel_hi:[1,0,1]
	s_waitcnt lgkmcnt(0)
	v_pk_mul_f32 v[114:115], v[70:71], v[74:75] op_sel_hi:[0,1]
	v_pk_mul_f32 v[116:117], v[70:71], v[78:79] op_sel_hi:[0,1]
	v_pk_fma_f32 v[110:111], v[114:115], v[50:51], 0 op_sel_hi:[1,1,0]
	v_pk_fma_f32 v[112:113], v[114:115], v[66:67], 0 op_sel_hi:[1,1,0]
	v_pk_mul_f32 v[118:119], v[70:71], v[80:81] op_sel_hi:[0,1]
	ds_read_b128 v[30:33], v94 offset:16000
	v_pk_fma_f32 v[110:111], v[116:117], v[52:53], v[110:111]
	v_pk_fma_f32 v[112:113], v[116:117], v[68:69], v[112:113]
	v_pk_mul_f32 v[120:121], v[70:71], v[82:83] op_sel_hi:[0,1]
	ds_read_b128 v[26:29], v94 offset:16016
	v_pk_fma_f32 v[110:111], v[118:119], v[46:47], v[110:111]
	v_pk_fma_f32 v[112:113], v[118:119], v[62:63], v[112:113]
	v_pk_mul_f32 v[122:123], v[70:71], v[84:85] op_sel_hi:[0,1]
	ds_read_b128 v[22:25], v94 offset:16032
	v_pk_fma_f32 v[110:111], v[120:121], v[48:49], v[110:111]
	v_pk_fma_f32 v[112:113], v[120:121], v[64:65], v[112:113]
	v_pk_mul_f32 v[124:125], v[70:71], v[86:87] op_sel_hi:[0,1]
	ds_read_b128 v[18:21], v94 offset:16048
	v_pk_fma_f32 v[110:111], v[122:123], v[42:43], v[110:111]
	v_pk_fma_f32 v[112:113], v[122:123], v[58:59], v[112:113]
	v_pk_mul_f32 v[126:127], v[70:71], v[88:89] op_sel_hi:[0,1]
	ds_read_b128 v[2:5], v94 offset:16256
	v_pk_fma_f32 v[110:111], v[124:125], v[44:45], v[110:111]
	v_pk_fma_f32 v[112:113], v[124:125], v[60:61], v[112:113]
	v_pk_mul_f32 v[128:129], v[70:71], v[90:91] op_sel_hi:[0,1]
	ds_read_b128 v[6:9], v94 offset:16272
	v_pk_fma_f32 v[110:111], v[126:127], v[38:39], v[110:111]
	v_pk_fma_f32 v[112:113], v[126:127], v[54:55], v[112:113]
	ds_read_b128 v[14:17], v94 offset:16288
	v_pk_fma_f32 v[110:111], v[128:129], v[40:41], v[110:111]
	v_pk_fma_f32 v[112:113], v[128:129], v[56:57], v[112:113]
	ds_read_b128 v[10:13], v94 offset:16304
	v_add_f32_e32 v134, v110, v111
	v_add_f32_e32 v135, v112, v113
	ds_read_b32 v73, v95 offset:16512
	v_add_f32_dpp v134, v134, v134 quad_perm:[1,0,3,2] row_mask:0xf bank_mask:0xf bound_ctrl:1
	v_add_f32_dpp v135, v135, v135 quad_perm:[1,0,3,2] row_mask:0xf bank_mask:0xf bound_ctrl:1
	ds_read_b96 v[34:36], v1 offset:16768
	v_add_f32_dpp v134, v134, v134 quad_perm:[2,3,0,1] row_mask:0xf bank_mask:0xf bound_ctrl:1
	v_add_f32_dpp v135, v135, v135 quad_perm:[2,3,0,1] row_mask:0xf bank_mask:0xf bound_ctrl:1
	v_sub_f32_e32 v134, v0, v134
	v_mul_f32_e32 v134, v71, v134
	v_fma_f32 v135, v72, v134, v135
	v_cvt_pk_bf16_f32 v133, v135, v135
	v_pk_fma_f32 v[74:75], v[50:51], v[134:135], v[114:115] op_sel_hi:[1,0,1]
	v_pk_fma_f32 v[78:79], v[52:53], v[134:135], v[116:117] op_sel_hi:[1,0,1]
	global_store_short v147, v133, s[100:101]
	v_pk_fma_f32 v[80:81], v[46:47], v[134:135], v[118:119] op_sel_hi:[1,0,1]
	v_pk_fma_f32 v[82:83], v[48:49], v[134:135], v[120:121] op_sel_hi:[1,0,1]
	v_pk_fma_f32 v[84:85], v[42:43], v[134:135], v[122:123] op_sel_hi:[1,0,1]
	v_pk_fma_f32 v[86:87], v[44:45], v[134:135], v[124:125] op_sel_hi:[1,0,1]
	v_pk_fma_f32 v[88:89], v[38:39], v[134:135], v[126:127] op_sel_hi:[1,0,1]
	v_pk_fma_f32 v[90:91], v[40:41], v[134:135], v[128:129] op_sel_hi:[1,0,1]
	s_waitcnt lgkmcnt(0)
	v_pk_mul_f32 v[114:115], v[34:35], v[74:75] op_sel_hi:[0,1]
	v_pk_mul_f32 v[116:117], v[34:35], v[78:79] op_sel_hi:[0,1]
	v_pk_fma_f32 v[106:107], v[114:115], v[2:3], 0 op_sel_hi:[1,1,0]
	v_pk_fma_f32 v[108:109], v[114:115], v[30:31], 0 op_sel_hi:[1,1,0]
	v_pk_mul_f32 v[118:119], v[34:35], v[80:81] op_sel_hi:[0,1]
	ds_read_b128 v[66:69], v94 offset:16800
	v_pk_fma_f32 v[106:107], v[116:117], v[4:5], v[106:107]
	v_pk_fma_f32 v[108:109], v[116:117], v[32:33], v[108:109]
	v_pk_mul_f32 v[120:121], v[34:35], v[82:83] op_sel_hi:[0,1]
	ds_read_b128 v[62:65], v94 offset:16816
	v_pk_fma_f32 v[106:107], v[118:119], v[6:7], v[106:107]
	v_pk_fma_f32 v[108:109], v[118:119], v[26:27], v[108:109]
	v_pk_mul_f32 v[122:123], v[34:35], v[84:85] op_sel_hi:[0,1]
	ds_read_b128 v[58:61], v94 offset:16832
	v_pk_fma_f32 v[106:107], v[120:121], v[8:9], v[106:107]
	v_pk_fma_f32 v[108:109], v[120:121], v[28:29], v[108:109]
	v_pk_mul_f32 v[124:125], v[34:35], v[86:87] op_sel_hi:[0,1]
	ds_read_b128 v[54:57], v94 offset:16848
	v_pk_fma_f32 v[106:107], v[122:123], v[14:15], v[106:107]
	v_pk_fma_f32 v[108:109], v[122:123], v[22:23], v[108:109]
	v_pk_mul_f32 v[126:127], v[34:35], v[88:89] op_sel_hi:[0,1]
	ds_read_b128 v[50:53], v94 offset:17056
	v_pk_fma_f32 v[106:107], v[124:125], v[16:17], v[106:107]
	v_pk_fma_f32 v[108:109], v[124:125], v[24:25], v[108:109]
	v_pk_mul_f32 v[128:129], v[34:35], v[90:91] op_sel_hi:[0,1]
	ds_read_b128 v[46:49], v94 offset:17072
	v_pk_fma_f32 v[106:107], v[126:127], v[10:11], v[106:107]
	v_pk_fma_f32 v[108:109], v[126:127], v[18:19], v[108:109]
	ds_read_b128 v[42:45], v94 offset:17088
	v_pk_fma_f32 v[106:107], v[128:129], v[12:13], v[106:107]
	v_pk_fma_f32 v[108:109], v[128:129], v[20:21], v[108:109]
	ds_read_b128 v[38:41], v94 offset:17104
	v_add_f32_e32 v130, v106, v107
	v_add_f32_e32 v131, v108, v109
	ds_read_b32 v0, v95 offset:17312
	v_add_f32_dpp v130, v130, v130 quad_perm:[1,0,3,2] row_mask:0xf bank_mask:0xf bound_ctrl:1
	v_add_f32_dpp v131, v131, v131 quad_perm:[1,0,3,2] row_mask:0xf bank_mask:0xf bound_ctrl:1
	ds_read_b96 v[70:72], v1 offset:17568
	v_add_f32_dpp v130, v130, v130 quad_perm:[2,3,0,1] row_mask:0xf bank_mask:0xf bound_ctrl:1
	v_add_f32_dpp v131, v131, v131 quad_perm:[2,3,0,1] row_mask:0xf bank_mask:0xf bound_ctrl:1
	v_sub_f32_e32 v130, v73, v130
	v_mul_f32_e32 v130, v35, v130
	v_fma_f32 v131, v36, v130, v131
	v_cvt_pk_bf16_f32 v132, v131, v131
	v_pk_fma_f32 v[74:75], v[2:3], v[130:131], v[114:115] op_sel_hi:[1,0,1]
	v_pk_fma_f32 v[78:79], v[4:5], v[130:131], v[116:117] op_sel_hi:[1,0,1]
	global_store_short v148, v132, s[100:101]
	v_pk_fma_f32 v[80:81], v[6:7], v[130:131], v[118:119] op_sel_hi:[1,0,1]
	v_pk_fma_f32 v[82:83], v[8:9], v[130:131], v[120:121] op_sel_hi:[1,0,1]
	v_pk_fma_f32 v[84:85], v[14:15], v[130:131], v[122:123] op_sel_hi:[1,0,1]
	v_pk_fma_f32 v[86:87], v[16:17], v[130:131], v[124:125] op_sel_hi:[1,0,1]
	v_pk_fma_f32 v[88:89], v[10:11], v[130:131], v[126:127] op_sel_hi:[1,0,1]
	v_pk_fma_f32 v[90:91], v[12:13], v[130:131], v[128:129] op_sel_hi:[1,0,1]
	s_waitcnt lgkmcnt(0)
	v_pk_mul_f32 v[114:115], v[70:71], v[74:75] op_sel_hi:[0,1]
	v_pk_mul_f32 v[116:117], v[70:71], v[78:79] op_sel_hi:[0,1]
	v_pk_fma_f32 v[110:111], v[114:115], v[50:51], 0 op_sel_hi:[1,1,0]
	v_pk_fma_f32 v[112:113], v[114:115], v[66:67], 0 op_sel_hi:[1,1,0]
	v_pk_mul_f32 v[118:119], v[70:71], v[80:81] op_sel_hi:[0,1]
	ds_read_b128 v[30:33], v94 offset:17600
	v_pk_fma_f32 v[110:111], v[116:117], v[52:53], v[110:111]
	v_pk_fma_f32 v[112:113], v[116:117], v[68:69], v[112:113]
	v_pk_mul_f32 v[120:121], v[70:71], v[82:83] op_sel_hi:[0,1]
	ds_read_b128 v[26:29], v94 offset:17616
	v_pk_fma_f32 v[110:111], v[118:119], v[46:47], v[110:111]
	v_pk_fma_f32 v[112:113], v[118:119], v[62:63], v[112:113]
	v_pk_mul_f32 v[122:123], v[70:71], v[84:85] op_sel_hi:[0,1]
	ds_read_b128 v[22:25], v94 offset:17632
	v_pk_fma_f32 v[110:111], v[120:121], v[48:49], v[110:111]
	v_pk_fma_f32 v[112:113], v[120:121], v[64:65], v[112:113]
	v_pk_mul_f32 v[124:125], v[70:71], v[86:87] op_sel_hi:[0,1]
	ds_read_b128 v[18:21], v94 offset:17648
	v_pk_fma_f32 v[110:111], v[122:123], v[42:43], v[110:111]
	v_pk_fma_f32 v[112:113], v[122:123], v[58:59], v[112:113]
	v_pk_mul_f32 v[126:127], v[70:71], v[88:89] op_sel_hi:[0,1]
	ds_read_b128 v[2:5], v94 offset:17856
	v_pk_fma_f32 v[110:111], v[124:125], v[44:45], v[110:111]
	v_pk_fma_f32 v[112:113], v[124:125], v[60:61], v[112:113]
	v_pk_mul_f32 v[128:129], v[70:71], v[90:91] op_sel_hi:[0,1]
	ds_read_b128 v[6:9], v94 offset:17872
	v_pk_fma_f32 v[110:111], v[126:127], v[38:39], v[110:111]
	v_pk_fma_f32 v[112:113], v[126:127], v[54:55], v[112:113]
	ds_read_b128 v[14:17], v94 offset:17888
	v_pk_fma_f32 v[110:111], v[128:129], v[40:41], v[110:111]
	v_pk_fma_f32 v[112:113], v[128:129], v[56:57], v[112:113]
	ds_read_b128 v[10:13], v94 offset:17904
	v_add_f32_e32 v134, v110, v111
	v_add_f32_e32 v135, v112, v113
	ds_read_b32 v73, v95 offset:18112
	v_add_f32_dpp v134, v134, v134 quad_perm:[1,0,3,2] row_mask:0xf bank_mask:0xf bound_ctrl:1
	v_add_f32_dpp v135, v135, v135 quad_perm:[1,0,3,2] row_mask:0xf bank_mask:0xf bound_ctrl:1
	ds_read_b96 v[34:36], v1 offset:18368
	v_add_f32_dpp v134, v134, v134 quad_perm:[2,3,0,1] row_mask:0xf bank_mask:0xf bound_ctrl:1
	v_add_f32_dpp v135, v135, v135 quad_perm:[2,3,0,1] row_mask:0xf bank_mask:0xf bound_ctrl:1
	v_sub_f32_e32 v134, v0, v134
	v_mul_f32_e32 v134, v71, v134
	v_fma_f32 v135, v72, v134, v135
	v_cvt_pk_bf16_f32 v133, v135, v135
	v_pk_fma_f32 v[74:75], v[50:51], v[134:135], v[114:115] op_sel_hi:[1,0,1]
	v_pk_fma_f32 v[78:79], v[52:53], v[134:135], v[116:117] op_sel_hi:[1,0,1]
	global_store_short v149, v133, s[100:101]
	v_pk_fma_f32 v[80:81], v[46:47], v[134:135], v[118:119] op_sel_hi:[1,0,1]
	v_pk_fma_f32 v[82:83], v[48:49], v[134:135], v[120:121] op_sel_hi:[1,0,1]
	v_pk_fma_f32 v[84:85], v[42:43], v[134:135], v[122:123] op_sel_hi:[1,0,1]
	v_pk_fma_f32 v[86:87], v[44:45], v[134:135], v[124:125] op_sel_hi:[1,0,1]
	v_pk_fma_f32 v[88:89], v[38:39], v[134:135], v[126:127] op_sel_hi:[1,0,1]
	v_pk_fma_f32 v[90:91], v[40:41], v[134:135], v[128:129] op_sel_hi:[1,0,1]
	s_waitcnt lgkmcnt(0)
	v_pk_mul_f32 v[114:115], v[34:35], v[74:75] op_sel_hi:[0,1]
	v_pk_mul_f32 v[116:117], v[34:35], v[78:79] op_sel_hi:[0,1]
	v_pk_fma_f32 v[106:107], v[114:115], v[2:3], 0 op_sel_hi:[1,1,0]
	v_pk_fma_f32 v[108:109], v[114:115], v[30:31], 0 op_sel_hi:[1,1,0]
	v_pk_mul_f32 v[118:119], v[34:35], v[80:81] op_sel_hi:[0,1]
	ds_read_b128 v[66:69], v94 offset:18400
	v_pk_fma_f32 v[106:107], v[116:117], v[4:5], v[106:107]
	v_pk_fma_f32 v[108:109], v[116:117], v[32:33], v[108:109]
	v_pk_mul_f32 v[120:121], v[34:35], v[82:83] op_sel_hi:[0,1]
	ds_read_b128 v[62:65], v94 offset:18416
	v_pk_fma_f32 v[106:107], v[118:119], v[6:7], v[106:107]
	v_pk_fma_f32 v[108:109], v[118:119], v[26:27], v[108:109]
	v_pk_mul_f32 v[122:123], v[34:35], v[84:85] op_sel_hi:[0,1]
	ds_read_b128 v[58:61], v94 offset:18432
	v_pk_fma_f32 v[106:107], v[120:121], v[8:9], v[106:107]
	v_pk_fma_f32 v[108:109], v[120:121], v[28:29], v[108:109]
	v_pk_mul_f32 v[124:125], v[34:35], v[86:87] op_sel_hi:[0,1]
	ds_read_b128 v[54:57], v94 offset:18448
	v_pk_fma_f32 v[106:107], v[122:123], v[14:15], v[106:107]
	v_pk_fma_f32 v[108:109], v[122:123], v[22:23], v[108:109]
	v_pk_mul_f32 v[126:127], v[34:35], v[88:89] op_sel_hi:[0,1]
	ds_read_b128 v[50:53], v94 offset:18656
	v_pk_fma_f32 v[106:107], v[124:125], v[16:17], v[106:107]
	v_pk_fma_f32 v[108:109], v[124:125], v[24:25], v[108:109]
	v_pk_mul_f32 v[128:129], v[34:35], v[90:91] op_sel_hi:[0,1]
	ds_read_b128 v[46:49], v94 offset:18672
	v_pk_fma_f32 v[106:107], v[126:127], v[10:11], v[106:107]
	v_pk_fma_f32 v[108:109], v[126:127], v[18:19], v[108:109]
	ds_read_b128 v[42:45], v94 offset:18688
	v_pk_fma_f32 v[106:107], v[128:129], v[12:13], v[106:107]
	v_pk_fma_f32 v[108:109], v[128:129], v[20:21], v[108:109]
	ds_read_b128 v[38:41], v94 offset:18704
	v_add_f32_e32 v130, v106, v107
	v_add_f32_e32 v131, v108, v109
	ds_read_b32 v0, v95 offset:18912
	v_add_f32_dpp v130, v130, v130 quad_perm:[1,0,3,2] row_mask:0xf bank_mask:0xf bound_ctrl:1
	v_add_f32_dpp v131, v131, v131 quad_perm:[1,0,3,2] row_mask:0xf bank_mask:0xf bound_ctrl:1
	ds_read_b96 v[70:72], v1 offset:19168
	v_add_f32_dpp v130, v130, v130 quad_perm:[2,3,0,1] row_mask:0xf bank_mask:0xf bound_ctrl:1
	v_add_f32_dpp v131, v131, v131 quad_perm:[2,3,0,1] row_mask:0xf bank_mask:0xf bound_ctrl:1
	v_sub_f32_e32 v130, v73, v130
	v_mul_f32_e32 v130, v35, v130
	v_fma_f32 v131, v36, v130, v131
	v_cvt_pk_bf16_f32 v132, v131, v131
	v_pk_fma_f32 v[74:75], v[2:3], v[130:131], v[114:115] op_sel_hi:[1,0,1]
	v_pk_fma_f32 v[78:79], v[4:5], v[130:131], v[116:117] op_sel_hi:[1,0,1]
	global_store_short v150, v132, s[100:101]
	v_pk_fma_f32 v[80:81], v[6:7], v[130:131], v[118:119] op_sel_hi:[1,0,1]
	v_pk_fma_f32 v[82:83], v[8:9], v[130:131], v[120:121] op_sel_hi:[1,0,1]
	v_pk_fma_f32 v[84:85], v[14:15], v[130:131], v[122:123] op_sel_hi:[1,0,1]
	v_pk_fma_f32 v[86:87], v[16:17], v[130:131], v[124:125] op_sel_hi:[1,0,1]
	v_pk_fma_f32 v[88:89], v[10:11], v[130:131], v[126:127] op_sel_hi:[1,0,1]
	v_pk_fma_f32 v[90:91], v[12:13], v[130:131], v[128:129] op_sel_hi:[1,0,1]
	s_waitcnt lgkmcnt(0)
	v_pk_mul_f32 v[114:115], v[70:71], v[74:75] op_sel_hi:[0,1]
	v_pk_mul_f32 v[116:117], v[70:71], v[78:79] op_sel_hi:[0,1]
	v_pk_fma_f32 v[110:111], v[114:115], v[50:51], 0 op_sel_hi:[1,1,0]
	v_pk_fma_f32 v[112:113], v[114:115], v[66:67], 0 op_sel_hi:[1,1,0]
	v_pk_mul_f32 v[118:119], v[70:71], v[80:81] op_sel_hi:[0,1]
	ds_read_b128 v[30:33], v94 offset:19200
	v_pk_fma_f32 v[110:111], v[116:117], v[52:53], v[110:111]
	v_pk_fma_f32 v[112:113], v[116:117], v[68:69], v[112:113]
	v_pk_mul_f32 v[120:121], v[70:71], v[82:83] op_sel_hi:[0,1]
	ds_read_b128 v[26:29], v94 offset:19216
	v_pk_fma_f32 v[110:111], v[118:119], v[46:47], v[110:111]
	v_pk_fma_f32 v[112:113], v[118:119], v[62:63], v[112:113]
	v_pk_mul_f32 v[122:123], v[70:71], v[84:85] op_sel_hi:[0,1]
	ds_read_b128 v[22:25], v94 offset:19232
	v_pk_fma_f32 v[110:111], v[120:121], v[48:49], v[110:111]
	v_pk_fma_f32 v[112:113], v[120:121], v[64:65], v[112:113]
	v_pk_mul_f32 v[124:125], v[70:71], v[86:87] op_sel_hi:[0,1]
	ds_read_b128 v[18:21], v94 offset:19248
	v_pk_fma_f32 v[110:111], v[122:123], v[42:43], v[110:111]
	v_pk_fma_f32 v[112:113], v[122:123], v[58:59], v[112:113]
	v_pk_mul_f32 v[126:127], v[70:71], v[88:89] op_sel_hi:[0,1]
	ds_read_b128 v[2:5], v94 offset:19456
	v_pk_fma_f32 v[110:111], v[124:125], v[44:45], v[110:111]
	v_pk_fma_f32 v[112:113], v[124:125], v[60:61], v[112:113]
	v_pk_mul_f32 v[128:129], v[70:71], v[90:91] op_sel_hi:[0,1]
	ds_read_b128 v[6:9], v94 offset:19472
	v_pk_fma_f32 v[110:111], v[126:127], v[38:39], v[110:111]
	v_pk_fma_f32 v[112:113], v[126:127], v[54:55], v[112:113]
	ds_read_b128 v[14:17], v94 offset:19488
	v_pk_fma_f32 v[110:111], v[128:129], v[40:41], v[110:111]
	v_pk_fma_f32 v[112:113], v[128:129], v[56:57], v[112:113]
	ds_read_b128 v[10:13], v94 offset:19504
	v_add_f32_e32 v134, v110, v111
	v_add_f32_e32 v135, v112, v113
	ds_read_b32 v73, v95 offset:19712
	v_add_f32_dpp v134, v134, v134 quad_perm:[1,0,3,2] row_mask:0xf bank_mask:0xf bound_ctrl:1
	v_add_f32_dpp v135, v135, v135 quad_perm:[1,0,3,2] row_mask:0xf bank_mask:0xf bound_ctrl:1
	ds_read_b96 v[34:36], v1 offset:19968
	v_add_f32_dpp v134, v134, v134 quad_perm:[2,3,0,1] row_mask:0xf bank_mask:0xf bound_ctrl:1
	v_add_f32_dpp v135, v135, v135 quad_perm:[2,3,0,1] row_mask:0xf bank_mask:0xf bound_ctrl:1
	v_sub_f32_e32 v134, v0, v134
	v_mul_f32_e32 v134, v71, v134
	v_fma_f32 v135, v72, v134, v135
	v_cvt_pk_bf16_f32 v133, v135, v135
	v_pk_fma_f32 v[74:75], v[50:51], v[134:135], v[114:115] op_sel_hi:[1,0,1]
	v_pk_fma_f32 v[78:79], v[52:53], v[134:135], v[116:117] op_sel_hi:[1,0,1]
	global_store_short v151, v133, s[100:101]
	v_pk_fma_f32 v[80:81], v[46:47], v[134:135], v[118:119] op_sel_hi:[1,0,1]
	v_pk_fma_f32 v[82:83], v[48:49], v[134:135], v[120:121] op_sel_hi:[1,0,1]
	v_pk_fma_f32 v[84:85], v[42:43], v[134:135], v[122:123] op_sel_hi:[1,0,1]
	v_pk_fma_f32 v[86:87], v[44:45], v[134:135], v[124:125] op_sel_hi:[1,0,1]
	v_pk_fma_f32 v[88:89], v[38:39], v[134:135], v[126:127] op_sel_hi:[1,0,1]
	v_pk_fma_f32 v[90:91], v[40:41], v[134:135], v[128:129] op_sel_hi:[1,0,1]
	s_waitcnt lgkmcnt(0)
	v_pk_mul_f32 v[114:115], v[34:35], v[74:75] op_sel_hi:[0,1]
	v_pk_mul_f32 v[116:117], v[34:35], v[78:79] op_sel_hi:[0,1]
	v_pk_fma_f32 v[106:107], v[114:115], v[2:3], 0 op_sel_hi:[1,1,0]
	v_pk_fma_f32 v[108:109], v[114:115], v[30:31], 0 op_sel_hi:[1,1,0]
	v_pk_mul_f32 v[118:119], v[34:35], v[80:81] op_sel_hi:[0,1]
	ds_read_b128 v[66:69], v94 offset:20000
	v_pk_fma_f32 v[106:107], v[116:117], v[4:5], v[106:107]
	v_pk_fma_f32 v[108:109], v[116:117], v[32:33], v[108:109]
	v_pk_mul_f32 v[120:121], v[34:35], v[82:83] op_sel_hi:[0,1]
	ds_read_b128 v[62:65], v94 offset:20016
	v_pk_fma_f32 v[106:107], v[118:119], v[6:7], v[106:107]
	v_pk_fma_f32 v[108:109], v[118:119], v[26:27], v[108:109]
	v_pk_mul_f32 v[122:123], v[34:35], v[84:85] op_sel_hi:[0,1]
	ds_read_b128 v[58:61], v94 offset:20032
	v_pk_fma_f32 v[106:107], v[120:121], v[8:9], v[106:107]
	v_pk_fma_f32 v[108:109], v[120:121], v[28:29], v[108:109]
	v_pk_mul_f32 v[124:125], v[34:35], v[86:87] op_sel_hi:[0,1]
	ds_read_b128 v[54:57], v94 offset:20048
	v_pk_fma_f32 v[106:107], v[122:123], v[14:15], v[106:107]
	v_pk_fma_f32 v[108:109], v[122:123], v[22:23], v[108:109]
	v_pk_mul_f32 v[126:127], v[34:35], v[88:89] op_sel_hi:[0,1]
	ds_read_b128 v[50:53], v94 offset:20256
	v_pk_fma_f32 v[106:107], v[124:125], v[16:17], v[106:107]
	v_pk_fma_f32 v[108:109], v[124:125], v[24:25], v[108:109]
	v_pk_mul_f32 v[128:129], v[34:35], v[90:91] op_sel_hi:[0,1]
	ds_read_b128 v[46:49], v94 offset:20272
	v_pk_fma_f32 v[106:107], v[126:127], v[10:11], v[106:107]
	v_pk_fma_f32 v[108:109], v[126:127], v[18:19], v[108:109]
	ds_read_b128 v[42:45], v94 offset:20288
	v_pk_fma_f32 v[106:107], v[128:129], v[12:13], v[106:107]
	v_pk_fma_f32 v[108:109], v[128:129], v[20:21], v[108:109]
	ds_read_b128 v[38:41], v94 offset:20304
	v_add_f32_e32 v130, v106, v107
	v_add_f32_e32 v131, v108, v109
	ds_read_b32 v0, v95 offset:20512
	v_add_f32_dpp v130, v130, v130 quad_perm:[1,0,3,2] row_mask:0xf bank_mask:0xf bound_ctrl:1
	v_add_f32_dpp v131, v131, v131 quad_perm:[1,0,3,2] row_mask:0xf bank_mask:0xf bound_ctrl:1
	ds_read_b96 v[70:72], v1 offset:20768
	v_add_f32_dpp v130, v130, v130 quad_perm:[2,3,0,1] row_mask:0xf bank_mask:0xf bound_ctrl:1
	v_add_f32_dpp v131, v131, v131 quad_perm:[2,3,0,1] row_mask:0xf bank_mask:0xf bound_ctrl:1
	v_sub_f32_e32 v130, v73, v130
	v_mul_f32_e32 v130, v35, v130
	v_fma_f32 v131, v36, v130, v131
	v_cvt_pk_bf16_f32 v132, v131, v131
	v_pk_fma_f32 v[74:75], v[2:3], v[130:131], v[114:115] op_sel_hi:[1,0,1]
	v_pk_fma_f32 v[78:79], v[4:5], v[130:131], v[116:117] op_sel_hi:[1,0,1]
	global_store_short v152, v132, s[100:101]
	v_pk_fma_f32 v[80:81], v[6:7], v[130:131], v[118:119] op_sel_hi:[1,0,1]
	v_pk_fma_f32 v[82:83], v[8:9], v[130:131], v[120:121] op_sel_hi:[1,0,1]
	v_pk_fma_f32 v[84:85], v[14:15], v[130:131], v[122:123] op_sel_hi:[1,0,1]
	v_pk_fma_f32 v[86:87], v[16:17], v[130:131], v[124:125] op_sel_hi:[1,0,1]
	v_pk_fma_f32 v[88:89], v[10:11], v[130:131], v[126:127] op_sel_hi:[1,0,1]
	v_pk_fma_f32 v[90:91], v[12:13], v[130:131], v[128:129] op_sel_hi:[1,0,1]
	s_waitcnt lgkmcnt(0)
	v_pk_mul_f32 v[114:115], v[70:71], v[74:75] op_sel_hi:[0,1]
	v_pk_mul_f32 v[116:117], v[70:71], v[78:79] op_sel_hi:[0,1]
	v_pk_fma_f32 v[110:111], v[114:115], v[50:51], 0 op_sel_hi:[1,1,0]
	v_pk_fma_f32 v[112:113], v[114:115], v[66:67], 0 op_sel_hi:[1,1,0]
	v_pk_mul_f32 v[118:119], v[70:71], v[80:81] op_sel_hi:[0,1]
	ds_read_b128 v[30:33], v94 offset:20800
	v_pk_fma_f32 v[110:111], v[116:117], v[52:53], v[110:111]
	v_pk_fma_f32 v[112:113], v[116:117], v[68:69], v[112:113]
	v_pk_mul_f32 v[120:121], v[70:71], v[82:83] op_sel_hi:[0,1]
	ds_read_b128 v[26:29], v94 offset:20816
	v_pk_fma_f32 v[110:111], v[118:119], v[46:47], v[110:111]
	v_pk_fma_f32 v[112:113], v[118:119], v[62:63], v[112:113]
	v_pk_mul_f32 v[122:123], v[70:71], v[84:85] op_sel_hi:[0,1]
	ds_read_b128 v[22:25], v94 offset:20832
	v_pk_fma_f32 v[110:111], v[120:121], v[48:49], v[110:111]
	v_pk_fma_f32 v[112:113], v[120:121], v[64:65], v[112:113]
	v_pk_mul_f32 v[124:125], v[70:71], v[86:87] op_sel_hi:[0,1]
	ds_read_b128 v[18:21], v94 offset:20848
	v_pk_fma_f32 v[110:111], v[122:123], v[42:43], v[110:111]
	v_pk_fma_f32 v[112:113], v[122:123], v[58:59], v[112:113]
	v_pk_mul_f32 v[126:127], v[70:71], v[88:89] op_sel_hi:[0,1]
	ds_read_b128 v[2:5], v94 offset:21056
	v_pk_fma_f32 v[110:111], v[124:125], v[44:45], v[110:111]
	v_pk_fma_f32 v[112:113], v[124:125], v[60:61], v[112:113]
	v_pk_mul_f32 v[128:129], v[70:71], v[90:91] op_sel_hi:[0,1]
	ds_read_b128 v[6:9], v94 offset:21072
	v_pk_fma_f32 v[110:111], v[126:127], v[38:39], v[110:111]
	v_pk_fma_f32 v[112:113], v[126:127], v[54:55], v[112:113]
	ds_read_b128 v[14:17], v94 offset:21088
	v_pk_fma_f32 v[110:111], v[128:129], v[40:41], v[110:111]
	v_pk_fma_f32 v[112:113], v[128:129], v[56:57], v[112:113]
	ds_read_b128 v[10:13], v94 offset:21104
	v_add_f32_e32 v134, v110, v111
	v_add_f32_e32 v135, v112, v113
	ds_read_b32 v73, v95 offset:21312
	v_add_f32_dpp v134, v134, v134 quad_perm:[1,0,3,2] row_mask:0xf bank_mask:0xf bound_ctrl:1
	v_add_f32_dpp v135, v135, v135 quad_perm:[1,0,3,2] row_mask:0xf bank_mask:0xf bound_ctrl:1
	ds_read_b96 v[34:36], v1 offset:21568
	v_add_f32_dpp v134, v134, v134 quad_perm:[2,3,0,1] row_mask:0xf bank_mask:0xf bound_ctrl:1
	v_add_f32_dpp v135, v135, v135 quad_perm:[2,3,0,1] row_mask:0xf bank_mask:0xf bound_ctrl:1
	v_sub_f32_e32 v134, v0, v134
	v_mul_f32_e32 v134, v71, v134
	v_fma_f32 v135, v72, v134, v135
	v_cvt_pk_bf16_f32 v133, v135, v135
	v_pk_fma_f32 v[74:75], v[50:51], v[134:135], v[114:115] op_sel_hi:[1,0,1]
	v_pk_fma_f32 v[78:79], v[52:53], v[134:135], v[116:117] op_sel_hi:[1,0,1]
	global_store_short v153, v133, s[100:101]
	v_pk_fma_f32 v[80:81], v[46:47], v[134:135], v[118:119] op_sel_hi:[1,0,1]
	v_pk_fma_f32 v[82:83], v[48:49], v[134:135], v[120:121] op_sel_hi:[1,0,1]
	v_pk_fma_f32 v[84:85], v[42:43], v[134:135], v[122:123] op_sel_hi:[1,0,1]
	v_pk_fma_f32 v[86:87], v[44:45], v[134:135], v[124:125] op_sel_hi:[1,0,1]
	v_pk_fma_f32 v[88:89], v[38:39], v[134:135], v[126:127] op_sel_hi:[1,0,1]
	v_pk_fma_f32 v[90:91], v[40:41], v[134:135], v[128:129] op_sel_hi:[1,0,1]
	s_waitcnt lgkmcnt(0)
	v_pk_mul_f32 v[114:115], v[34:35], v[74:75] op_sel_hi:[0,1]
	v_pk_mul_f32 v[116:117], v[34:35], v[78:79] op_sel_hi:[0,1]
	v_pk_fma_f32 v[106:107], v[114:115], v[2:3], 0 op_sel_hi:[1,1,0]
	v_pk_fma_f32 v[108:109], v[114:115], v[30:31], 0 op_sel_hi:[1,1,0]
	v_pk_mul_f32 v[118:119], v[34:35], v[80:81] op_sel_hi:[0,1]
	ds_read_b128 v[66:69], v94 offset:21600
	v_pk_fma_f32 v[106:107], v[116:117], v[4:5], v[106:107]
	v_pk_fma_f32 v[108:109], v[116:117], v[32:33], v[108:109]
	v_pk_mul_f32 v[120:121], v[34:35], v[82:83] op_sel_hi:[0,1]
	ds_read_b128 v[62:65], v94 offset:21616
	v_pk_fma_f32 v[106:107], v[118:119], v[6:7], v[106:107]
	v_pk_fma_f32 v[108:109], v[118:119], v[26:27], v[108:109]
	v_pk_mul_f32 v[122:123], v[34:35], v[84:85] op_sel_hi:[0,1]
	ds_read_b128 v[58:61], v94 offset:21632
	v_pk_fma_f32 v[106:107], v[120:121], v[8:9], v[106:107]
	v_pk_fma_f32 v[108:109], v[120:121], v[28:29], v[108:109]
	v_pk_mul_f32 v[124:125], v[34:35], v[86:87] op_sel_hi:[0,1]
	ds_read_b128 v[54:57], v94 offset:21648
	v_pk_fma_f32 v[106:107], v[122:123], v[14:15], v[106:107]
	v_pk_fma_f32 v[108:109], v[122:123], v[22:23], v[108:109]
	v_pk_mul_f32 v[126:127], v[34:35], v[88:89] op_sel_hi:[0,1]
	ds_read_b128 v[50:53], v94 offset:21856
	v_pk_fma_f32 v[106:107], v[124:125], v[16:17], v[106:107]
	v_pk_fma_f32 v[108:109], v[124:125], v[24:25], v[108:109]
	v_pk_mul_f32 v[128:129], v[34:35], v[90:91] op_sel_hi:[0,1]
	ds_read_b128 v[46:49], v94 offset:21872
	v_pk_fma_f32 v[106:107], v[126:127], v[10:11], v[106:107]
	v_pk_fma_f32 v[108:109], v[126:127], v[18:19], v[108:109]
	ds_read_b128 v[42:45], v94 offset:21888
	v_pk_fma_f32 v[106:107], v[128:129], v[12:13], v[106:107]
	v_pk_fma_f32 v[108:109], v[128:129], v[20:21], v[108:109]
	ds_read_b128 v[38:41], v94 offset:21904
	v_add_f32_e32 v130, v106, v107
	v_add_f32_e32 v131, v108, v109
	ds_read_b32 v0, v95 offset:22112
	v_add_f32_dpp v130, v130, v130 quad_perm:[1,0,3,2] row_mask:0xf bank_mask:0xf bound_ctrl:1
	v_add_f32_dpp v131, v131, v131 quad_perm:[1,0,3,2] row_mask:0xf bank_mask:0xf bound_ctrl:1
	ds_read_b96 v[70:72], v1 offset:22368
	v_add_f32_dpp v130, v130, v130 quad_perm:[2,3,0,1] row_mask:0xf bank_mask:0xf bound_ctrl:1
	v_add_f32_dpp v131, v131, v131 quad_perm:[2,3,0,1] row_mask:0xf bank_mask:0xf bound_ctrl:1
	v_sub_f32_e32 v130, v73, v130
	v_mul_f32_e32 v130, v35, v130
	v_fma_f32 v131, v36, v130, v131
	v_cvt_pk_bf16_f32 v132, v131, v131
	v_pk_fma_f32 v[74:75], v[2:3], v[130:131], v[114:115] op_sel_hi:[1,0,1]
	v_pk_fma_f32 v[78:79], v[4:5], v[130:131], v[116:117] op_sel_hi:[1,0,1]
	global_store_short v154, v132, s[100:101]
	v_pk_fma_f32 v[80:81], v[6:7], v[130:131], v[118:119] op_sel_hi:[1,0,1]
	v_pk_fma_f32 v[82:83], v[8:9], v[130:131], v[120:121] op_sel_hi:[1,0,1]
	v_pk_fma_f32 v[84:85], v[14:15], v[130:131], v[122:123] op_sel_hi:[1,0,1]
	v_pk_fma_f32 v[86:87], v[16:17], v[130:131], v[124:125] op_sel_hi:[1,0,1]
	v_pk_fma_f32 v[88:89], v[10:11], v[130:131], v[126:127] op_sel_hi:[1,0,1]
	v_pk_fma_f32 v[90:91], v[12:13], v[130:131], v[128:129] op_sel_hi:[1,0,1]
	s_waitcnt lgkmcnt(0)
	v_pk_mul_f32 v[114:115], v[70:71], v[74:75] op_sel_hi:[0,1]
	v_pk_mul_f32 v[116:117], v[70:71], v[78:79] op_sel_hi:[0,1]
	v_pk_fma_f32 v[110:111], v[114:115], v[50:51], 0 op_sel_hi:[1,1,0]
	v_pk_fma_f32 v[112:113], v[114:115], v[66:67], 0 op_sel_hi:[1,1,0]
	v_pk_mul_f32 v[118:119], v[70:71], v[80:81] op_sel_hi:[0,1]
	ds_read_b128 v[30:33], v94 offset:22400
	v_pk_fma_f32 v[110:111], v[116:117], v[52:53], v[110:111]
	v_pk_fma_f32 v[112:113], v[116:117], v[68:69], v[112:113]
	v_pk_mul_f32 v[120:121], v[70:71], v[82:83] op_sel_hi:[0,1]
	ds_read_b128 v[26:29], v94 offset:22416
	v_pk_fma_f32 v[110:111], v[118:119], v[46:47], v[110:111]
	v_pk_fma_f32 v[112:113], v[118:119], v[62:63], v[112:113]
	v_pk_mul_f32 v[122:123], v[70:71], v[84:85] op_sel_hi:[0,1]
	ds_read_b128 v[22:25], v94 offset:22432
	v_pk_fma_f32 v[110:111], v[120:121], v[48:49], v[110:111]
	v_pk_fma_f32 v[112:113], v[120:121], v[64:65], v[112:113]
	v_pk_mul_f32 v[124:125], v[70:71], v[86:87] op_sel_hi:[0,1]
	ds_read_b128 v[18:21], v94 offset:22448
	v_pk_fma_f32 v[110:111], v[122:123], v[42:43], v[110:111]
	v_pk_fma_f32 v[112:113], v[122:123], v[58:59], v[112:113]
	v_pk_mul_f32 v[126:127], v[70:71], v[88:89] op_sel_hi:[0,1]
	ds_read_b128 v[2:5], v94 offset:22656
	v_pk_fma_f32 v[110:111], v[124:125], v[44:45], v[110:111]
	v_pk_fma_f32 v[112:113], v[124:125], v[60:61], v[112:113]
	v_pk_mul_f32 v[128:129], v[70:71], v[90:91] op_sel_hi:[0,1]
	ds_read_b128 v[6:9], v94 offset:22672
	v_pk_fma_f32 v[110:111], v[126:127], v[38:39], v[110:111]
	v_pk_fma_f32 v[112:113], v[126:127], v[54:55], v[112:113]
	ds_read_b128 v[14:17], v94 offset:22688
	v_pk_fma_f32 v[110:111], v[128:129], v[40:41], v[110:111]
	v_pk_fma_f32 v[112:113], v[128:129], v[56:57], v[112:113]
	ds_read_b128 v[10:13], v94 offset:22704
	v_add_f32_e32 v134, v110, v111
	v_add_f32_e32 v135, v112, v113
	ds_read_b32 v73, v95 offset:22912
	v_add_f32_dpp v134, v134, v134 quad_perm:[1,0,3,2] row_mask:0xf bank_mask:0xf bound_ctrl:1
	v_add_f32_dpp v135, v135, v135 quad_perm:[1,0,3,2] row_mask:0xf bank_mask:0xf bound_ctrl:1
	ds_read_b96 v[34:36], v1 offset:23168
	v_add_f32_dpp v134, v134, v134 quad_perm:[2,3,0,1] row_mask:0xf bank_mask:0xf bound_ctrl:1
	v_add_f32_dpp v135, v135, v135 quad_perm:[2,3,0,1] row_mask:0xf bank_mask:0xf bound_ctrl:1
	v_sub_f32_e32 v134, v0, v134
	v_mul_f32_e32 v134, v71, v134
	v_fma_f32 v135, v72, v134, v135
	v_cvt_pk_bf16_f32 v133, v135, v135
	v_pk_fma_f32 v[74:75], v[50:51], v[134:135], v[114:115] op_sel_hi:[1,0,1]
	v_pk_fma_f32 v[78:79], v[52:53], v[134:135], v[116:117] op_sel_hi:[1,0,1]
	global_store_short v155, v133, s[100:101]
	v_pk_fma_f32 v[80:81], v[46:47], v[134:135], v[118:119] op_sel_hi:[1,0,1]
	v_pk_fma_f32 v[82:83], v[48:49], v[134:135], v[120:121] op_sel_hi:[1,0,1]
	v_pk_fma_f32 v[84:85], v[42:43], v[134:135], v[122:123] op_sel_hi:[1,0,1]
	v_pk_fma_f32 v[86:87], v[44:45], v[134:135], v[124:125] op_sel_hi:[1,0,1]
	v_pk_fma_f32 v[88:89], v[38:39], v[134:135], v[126:127] op_sel_hi:[1,0,1]
	v_pk_fma_f32 v[90:91], v[40:41], v[134:135], v[128:129] op_sel_hi:[1,0,1]
	s_waitcnt lgkmcnt(0)
	v_pk_mul_f32 v[114:115], v[34:35], v[74:75] op_sel_hi:[0,1]
	v_pk_mul_f32 v[116:117], v[34:35], v[78:79] op_sel_hi:[0,1]
	v_pk_fma_f32 v[106:107], v[114:115], v[2:3], 0 op_sel_hi:[1,1,0]
	v_pk_fma_f32 v[108:109], v[114:115], v[30:31], 0 op_sel_hi:[1,1,0]
	v_pk_mul_f32 v[118:119], v[34:35], v[80:81] op_sel_hi:[0,1]
	ds_read_b128 v[66:69], v94 offset:23200
	v_pk_fma_f32 v[106:107], v[116:117], v[4:5], v[106:107]
	v_pk_fma_f32 v[108:109], v[116:117], v[32:33], v[108:109]
	v_pk_mul_f32 v[120:121], v[34:35], v[82:83] op_sel_hi:[0,1]
	ds_read_b128 v[62:65], v94 offset:23216
	v_pk_fma_f32 v[106:107], v[118:119], v[6:7], v[106:107]
	v_pk_fma_f32 v[108:109], v[118:119], v[26:27], v[108:109]
	v_pk_mul_f32 v[122:123], v[34:35], v[84:85] op_sel_hi:[0,1]
	ds_read_b128 v[58:61], v94 offset:23232
	v_pk_fma_f32 v[106:107], v[120:121], v[8:9], v[106:107]
	v_pk_fma_f32 v[108:109], v[120:121], v[28:29], v[108:109]
	v_pk_mul_f32 v[124:125], v[34:35], v[86:87] op_sel_hi:[0,1]
	ds_read_b128 v[54:57], v94 offset:23248
	v_pk_fma_f32 v[106:107], v[122:123], v[14:15], v[106:107]
	v_pk_fma_f32 v[108:109], v[122:123], v[22:23], v[108:109]
	v_pk_mul_f32 v[126:127], v[34:35], v[88:89] op_sel_hi:[0,1]
	ds_read_b128 v[50:53], v94 offset:23456
	v_pk_fma_f32 v[106:107], v[124:125], v[16:17], v[106:107]
	v_pk_fma_f32 v[108:109], v[124:125], v[24:25], v[108:109]
	v_pk_mul_f32 v[128:129], v[34:35], v[90:91] op_sel_hi:[0,1]
	ds_read_b128 v[46:49], v94 offset:23472
	v_pk_fma_f32 v[106:107], v[126:127], v[10:11], v[106:107]
	v_pk_fma_f32 v[108:109], v[126:127], v[18:19], v[108:109]
	ds_read_b128 v[42:45], v94 offset:23488
	v_pk_fma_f32 v[106:107], v[128:129], v[12:13], v[106:107]
	v_pk_fma_f32 v[108:109], v[128:129], v[20:21], v[108:109]
	ds_read_b128 v[38:41], v94 offset:23504
	v_add_f32_e32 v130, v106, v107
	v_add_f32_e32 v131, v108, v109
	ds_read_b32 v0, v95 offset:23712
	v_add_f32_dpp v130, v130, v130 quad_perm:[1,0,3,2] row_mask:0xf bank_mask:0xf bound_ctrl:1
	v_add_f32_dpp v131, v131, v131 quad_perm:[1,0,3,2] row_mask:0xf bank_mask:0xf bound_ctrl:1
	ds_read_b96 v[70:72], v1 offset:23968
	v_add_f32_dpp v130, v130, v130 quad_perm:[2,3,0,1] row_mask:0xf bank_mask:0xf bound_ctrl:1
	v_add_f32_dpp v131, v131, v131 quad_perm:[2,3,0,1] row_mask:0xf bank_mask:0xf bound_ctrl:1
	v_sub_f32_e32 v130, v73, v130
	v_mul_f32_e32 v130, v35, v130
	v_fma_f32 v131, v36, v130, v131
	v_cvt_pk_bf16_f32 v132, v131, v131
	v_pk_fma_f32 v[74:75], v[2:3], v[130:131], v[114:115] op_sel_hi:[1,0,1]
	v_pk_fma_f32 v[78:79], v[4:5], v[130:131], v[116:117] op_sel_hi:[1,0,1]
	global_store_short v156, v132, s[100:101]
	v_pk_fma_f32 v[80:81], v[6:7], v[130:131], v[118:119] op_sel_hi:[1,0,1]
	v_pk_fma_f32 v[82:83], v[8:9], v[130:131], v[120:121] op_sel_hi:[1,0,1]
	v_pk_fma_f32 v[84:85], v[14:15], v[130:131], v[122:123] op_sel_hi:[1,0,1]
	v_pk_fma_f32 v[86:87], v[16:17], v[130:131], v[124:125] op_sel_hi:[1,0,1]
	v_pk_fma_f32 v[88:89], v[10:11], v[130:131], v[126:127] op_sel_hi:[1,0,1]
	v_pk_fma_f32 v[90:91], v[12:13], v[130:131], v[128:129] op_sel_hi:[1,0,1]
	s_waitcnt lgkmcnt(0)
	v_pk_mul_f32 v[114:115], v[70:71], v[74:75] op_sel_hi:[0,1]
	v_pk_mul_f32 v[116:117], v[70:71], v[78:79] op_sel_hi:[0,1]
	v_pk_fma_f32 v[110:111], v[114:115], v[50:51], 0 op_sel_hi:[1,1,0]
	v_pk_fma_f32 v[112:113], v[114:115], v[66:67], 0 op_sel_hi:[1,1,0]
	v_pk_mul_f32 v[118:119], v[70:71], v[80:81] op_sel_hi:[0,1]
	ds_read_b128 v[30:33], v94 offset:24000
	v_pk_fma_f32 v[110:111], v[116:117], v[52:53], v[110:111]
	v_pk_fma_f32 v[112:113], v[116:117], v[68:69], v[112:113]
	v_pk_mul_f32 v[120:121], v[70:71], v[82:83] op_sel_hi:[0,1]
	ds_read_b128 v[26:29], v94 offset:24016
	v_pk_fma_f32 v[110:111], v[118:119], v[46:47], v[110:111]
	v_pk_fma_f32 v[112:113], v[118:119], v[62:63], v[112:113]
	v_pk_mul_f32 v[122:123], v[70:71], v[84:85] op_sel_hi:[0,1]
	ds_read_b128 v[22:25], v94 offset:24032
	v_pk_fma_f32 v[110:111], v[120:121], v[48:49], v[110:111]
	v_pk_fma_f32 v[112:113], v[120:121], v[64:65], v[112:113]
	v_pk_mul_f32 v[124:125], v[70:71], v[86:87] op_sel_hi:[0,1]
	ds_read_b128 v[18:21], v94 offset:24048
	v_pk_fma_f32 v[110:111], v[122:123], v[42:43], v[110:111]
	v_pk_fma_f32 v[112:113], v[122:123], v[58:59], v[112:113]
	v_pk_mul_f32 v[126:127], v[70:71], v[88:89] op_sel_hi:[0,1]
	ds_read_b128 v[2:5], v94 offset:24256
	v_pk_fma_f32 v[110:111], v[124:125], v[44:45], v[110:111]
	v_pk_fma_f32 v[112:113], v[124:125], v[60:61], v[112:113]
	v_pk_mul_f32 v[128:129], v[70:71], v[90:91] op_sel_hi:[0,1]
	ds_read_b128 v[6:9], v94 offset:24272
	v_pk_fma_f32 v[110:111], v[126:127], v[38:39], v[110:111]
	v_pk_fma_f32 v[112:113], v[126:127], v[54:55], v[112:113]
	ds_read_b128 v[14:17], v94 offset:24288
	v_pk_fma_f32 v[110:111], v[128:129], v[40:41], v[110:111]
	v_pk_fma_f32 v[112:113], v[128:129], v[56:57], v[112:113]
	ds_read_b128 v[10:13], v94 offset:24304
	v_add_f32_e32 v134, v110, v111
	v_add_f32_e32 v135, v112, v113
	ds_read_b32 v73, v95 offset:24512
	v_add_f32_dpp v134, v134, v134 quad_perm:[1,0,3,2] row_mask:0xf bank_mask:0xf bound_ctrl:1
	v_add_f32_dpp v135, v135, v135 quad_perm:[1,0,3,2] row_mask:0xf bank_mask:0xf bound_ctrl:1
	ds_read_b96 v[34:36], v1 offset:24768
	v_add_f32_dpp v134, v134, v134 quad_perm:[2,3,0,1] row_mask:0xf bank_mask:0xf bound_ctrl:1
	v_add_f32_dpp v135, v135, v135 quad_perm:[2,3,0,1] row_mask:0xf bank_mask:0xf bound_ctrl:1
	v_sub_f32_e32 v134, v0, v134
	v_mul_f32_e32 v134, v71, v134
	v_fma_f32 v135, v72, v134, v135
	v_cvt_pk_bf16_f32 v133, v135, v135
	v_pk_fma_f32 v[74:75], v[50:51], v[134:135], v[114:115] op_sel_hi:[1,0,1]
	v_pk_fma_f32 v[78:79], v[52:53], v[134:135], v[116:117] op_sel_hi:[1,0,1]
	global_store_short v157, v133, s[100:101]
	v_pk_fma_f32 v[80:81], v[46:47], v[134:135], v[118:119] op_sel_hi:[1,0,1]
	v_pk_fma_f32 v[82:83], v[48:49], v[134:135], v[120:121] op_sel_hi:[1,0,1]
	v_pk_fma_f32 v[84:85], v[42:43], v[134:135], v[122:123] op_sel_hi:[1,0,1]
	v_pk_fma_f32 v[86:87], v[44:45], v[134:135], v[124:125] op_sel_hi:[1,0,1]
	v_pk_fma_f32 v[88:89], v[38:39], v[134:135], v[126:127] op_sel_hi:[1,0,1]
	v_pk_fma_f32 v[90:91], v[40:41], v[134:135], v[128:129] op_sel_hi:[1,0,1]
	s_waitcnt lgkmcnt(0)
	v_pk_mul_f32 v[114:115], v[34:35], v[74:75] op_sel_hi:[0,1]
	v_pk_mul_f32 v[116:117], v[34:35], v[78:79] op_sel_hi:[0,1]
	v_pk_fma_f32 v[106:107], v[114:115], v[2:3], 0 op_sel_hi:[1,1,0]
	v_pk_fma_f32 v[108:109], v[114:115], v[30:31], 0 op_sel_hi:[1,1,0]
	v_pk_mul_f32 v[118:119], v[34:35], v[80:81] op_sel_hi:[0,1]
	ds_read_b128 v[66:69], v94 offset:24800
	v_pk_fma_f32 v[106:107], v[116:117], v[4:5], v[106:107]
	v_pk_fma_f32 v[108:109], v[116:117], v[32:33], v[108:109]
	v_pk_mul_f32 v[120:121], v[34:35], v[82:83] op_sel_hi:[0,1]
	ds_read_b128 v[62:65], v94 offset:24816
	v_pk_fma_f32 v[106:107], v[118:119], v[6:7], v[106:107]
	v_pk_fma_f32 v[108:109], v[118:119], v[26:27], v[108:109]
	v_pk_mul_f32 v[122:123], v[34:35], v[84:85] op_sel_hi:[0,1]
	ds_read_b128 v[58:61], v94 offset:24832
	v_pk_fma_f32 v[106:107], v[120:121], v[8:9], v[106:107]
	v_pk_fma_f32 v[108:109], v[120:121], v[28:29], v[108:109]
	v_pk_mul_f32 v[124:125], v[34:35], v[86:87] op_sel_hi:[0,1]
	ds_read_b128 v[54:57], v94 offset:24848
	v_pk_fma_f32 v[106:107], v[122:123], v[14:15], v[106:107]
	v_pk_fma_f32 v[108:109], v[122:123], v[22:23], v[108:109]
	v_pk_mul_f32 v[126:127], v[34:35], v[88:89] op_sel_hi:[0,1]
	ds_read_b128 v[50:53], v94 offset:25056
	v_pk_fma_f32 v[106:107], v[124:125], v[16:17], v[106:107]
	v_pk_fma_f32 v[108:109], v[124:125], v[24:25], v[108:109]
	v_pk_mul_f32 v[128:129], v[34:35], v[90:91] op_sel_hi:[0,1]
	ds_read_b128 v[46:49], v94 offset:25072
	v_pk_fma_f32 v[106:107], v[126:127], v[10:11], v[106:107]
	v_pk_fma_f32 v[108:109], v[126:127], v[18:19], v[108:109]
	ds_read_b128 v[42:45], v94 offset:25088
	v_pk_fma_f32 v[106:107], v[128:129], v[12:13], v[106:107]
	v_pk_fma_f32 v[108:109], v[128:129], v[20:21], v[108:109]
	ds_read_b128 v[38:41], v94 offset:25104
	v_add_f32_e32 v130, v106, v107
	v_add_f32_e32 v131, v108, v109
	ds_read_b32 v0, v95 offset:25312
	v_add_f32_dpp v130, v130, v130 quad_perm:[1,0,3,2] row_mask:0xf bank_mask:0xf bound_ctrl:1
	v_add_f32_dpp v131, v131, v131 quad_perm:[1,0,3,2] row_mask:0xf bank_mask:0xf bound_ctrl:1
	ds_read_b96 v[70:72], v1 offset:25568
	v_add_f32_dpp v130, v130, v130 quad_perm:[2,3,0,1] row_mask:0xf bank_mask:0xf bound_ctrl:1
	v_add_f32_dpp v131, v131, v131 quad_perm:[2,3,0,1] row_mask:0xf bank_mask:0xf bound_ctrl:1
	v_sub_f32_e32 v130, v73, v130
	v_mul_f32_e32 v130, v35, v130
	v_fma_f32 v131, v36, v130, v131
	v_cvt_pk_bf16_f32 v132, v131, v131
	v_pk_fma_f32 v[74:75], v[2:3], v[130:131], v[114:115] op_sel_hi:[1,0,1]
	v_pk_fma_f32 v[78:79], v[4:5], v[130:131], v[116:117] op_sel_hi:[1,0,1]
	global_store_short v158, v132, s[100:101]
	v_pk_fma_f32 v[80:81], v[6:7], v[130:131], v[118:119] op_sel_hi:[1,0,1]
	v_pk_fma_f32 v[82:83], v[8:9], v[130:131], v[120:121] op_sel_hi:[1,0,1]
	v_pk_fma_f32 v[84:85], v[14:15], v[130:131], v[122:123] op_sel_hi:[1,0,1]
	v_pk_fma_f32 v[86:87], v[16:17], v[130:131], v[124:125] op_sel_hi:[1,0,1]
	v_pk_fma_f32 v[88:89], v[10:11], v[130:131], v[126:127] op_sel_hi:[1,0,1]
	v_pk_fma_f32 v[90:91], v[12:13], v[130:131], v[128:129] op_sel_hi:[1,0,1]
	s_waitcnt lgkmcnt(0)
	v_pk_mul_f32 v[114:115], v[70:71], v[74:75] op_sel_hi:[0,1]
	v_pk_mul_f32 v[116:117], v[70:71], v[78:79] op_sel_hi:[0,1]
	v_pk_fma_f32 v[110:111], v[114:115], v[50:51], 0 op_sel_hi:[1,1,0]
	v_pk_fma_f32 v[112:113], v[114:115], v[66:67], 0 op_sel_hi:[1,1,0]
	v_pk_mul_f32 v[118:119], v[70:71], v[80:81] op_sel_hi:[0,1]
	ds_read_b128 v[30:33], v94 offset:25600
	v_pk_fma_f32 v[110:111], v[116:117], v[52:53], v[110:111]
	v_pk_fma_f32 v[112:113], v[116:117], v[68:69], v[112:113]
	v_pk_mul_f32 v[120:121], v[70:71], v[82:83] op_sel_hi:[0,1]
	ds_read_b128 v[26:29], v94 offset:25616
	v_pk_fma_f32 v[110:111], v[118:119], v[46:47], v[110:111]
	v_pk_fma_f32 v[112:113], v[118:119], v[62:63], v[112:113]
	v_pk_mul_f32 v[122:123], v[70:71], v[84:85] op_sel_hi:[0,1]
	ds_read_b128 v[22:25], v94 offset:25632
	v_pk_fma_f32 v[110:111], v[120:121], v[48:49], v[110:111]
	v_pk_fma_f32 v[112:113], v[120:121], v[64:65], v[112:113]
	v_pk_mul_f32 v[124:125], v[70:71], v[86:87] op_sel_hi:[0,1]
	ds_read_b128 v[18:21], v94 offset:25648
	v_pk_fma_f32 v[110:111], v[122:123], v[42:43], v[110:111]
	v_pk_fma_f32 v[112:113], v[122:123], v[58:59], v[112:113]
	v_pk_mul_f32 v[126:127], v[70:71], v[88:89] op_sel_hi:[0,1]
	ds_read_b128 v[2:5], v94 offset:25856
	v_pk_fma_f32 v[110:111], v[124:125], v[44:45], v[110:111]
	v_pk_fma_f32 v[112:113], v[124:125], v[60:61], v[112:113]
	v_pk_mul_f32 v[128:129], v[70:71], v[90:91] op_sel_hi:[0,1]
	ds_read_b128 v[6:9], v94 offset:25872
	v_pk_fma_f32 v[110:111], v[126:127], v[38:39], v[110:111]
	v_pk_fma_f32 v[112:113], v[126:127], v[54:55], v[112:113]
	ds_read_b128 v[14:17], v94 offset:25888
	v_pk_fma_f32 v[110:111], v[128:129], v[40:41], v[110:111]
	v_pk_fma_f32 v[112:113], v[128:129], v[56:57], v[112:113]
	ds_read_b128 v[10:13], v94 offset:25904
	v_add_f32_e32 v134, v110, v111
	v_add_f32_e32 v135, v112, v113
	ds_read_b32 v73, v95 offset:26112
	v_add_f32_dpp v134, v134, v134 quad_perm:[1,0,3,2] row_mask:0xf bank_mask:0xf bound_ctrl:1
	v_add_f32_dpp v135, v135, v135 quad_perm:[1,0,3,2] row_mask:0xf bank_mask:0xf bound_ctrl:1
	ds_read_b96 v[34:36], v1 offset:26368
	v_add_f32_dpp v134, v134, v134 quad_perm:[2,3,0,1] row_mask:0xf bank_mask:0xf bound_ctrl:1
	v_add_f32_dpp v135, v135, v135 quad_perm:[2,3,0,1] row_mask:0xf bank_mask:0xf bound_ctrl:1
	v_sub_f32_e32 v134, v0, v134
	v_mul_f32_e32 v134, v71, v134
	v_fma_f32 v135, v72, v134, v135
	v_cvt_pk_bf16_f32 v133, v135, v135
	v_pk_fma_f32 v[74:75], v[50:51], v[134:135], v[114:115] op_sel_hi:[1,0,1]
	v_pk_fma_f32 v[78:79], v[52:53], v[134:135], v[116:117] op_sel_hi:[1,0,1]
	global_store_short v159, v133, s[100:101]
	v_pk_fma_f32 v[80:81], v[46:47], v[134:135], v[118:119] op_sel_hi:[1,0,1]
	v_pk_fma_f32 v[82:83], v[48:49], v[134:135], v[120:121] op_sel_hi:[1,0,1]
	v_pk_fma_f32 v[84:85], v[42:43], v[134:135], v[122:123] op_sel_hi:[1,0,1]
	v_pk_fma_f32 v[86:87], v[44:45], v[134:135], v[124:125] op_sel_hi:[1,0,1]
	v_pk_fma_f32 v[88:89], v[38:39], v[134:135], v[126:127] op_sel_hi:[1,0,1]
	v_pk_fma_f32 v[90:91], v[40:41], v[134:135], v[128:129] op_sel_hi:[1,0,1]
	s_branch .LBB0_899
